# row phases: wave_sum butterflies done with permlane32/16 swaps and DPP row rotations instead of six serial ds_bpermute round trips (bit-identical sums)
# speedup vs baseline: 1.0148x; 1.0148x over previous
.Lr0pfB_d:
	s_add_i32 s14, s14, 2
	s_cmp_eq_u32 s14, 4
	s_nop 0
	v_mov_b32_e32 v60, v73
	s_nop 0
	v_mov_b32_e32 v61, v77
	v_mov_b32_e32 v56, v72
	v_mov_b32_e32 v57, v76
	s_nop 0
	v_mov_b32_e32 v94, v81
	s_nop 0
	v_mov_b32_e32 v95, v85
	v_pk_mul_f32 v[60:61], v[60:61], v[60:61]
	v_mov_b32_e32 v88, v74
	v_mov_b32_e32 v89, v78
	v_mov_b32_e32 v92, v80
	v_mov_b32_e32 v93, v84
	v_pk_mul_f32 v[94:95], v[94:95], v[94:95]
	v_pk_fma_f32 v[56:57], v[56:57], v[56:57], v[60:61]
	v_mov_b32_e32 v90, v75
	v_mov_b32_e32 v91, v79
	v_mov_b32_e32 v96, v82
	v_mov_b32_e32 v97, v86
	v_pk_fma_f32 v[60:61], v[92:93], v[92:93], v[94:95]
	v_pk_fma_f32 v[56:57], v[88:89], v[88:89], v[56:57]
	v_mov_b32_e32 v98, v83
	v_mov_b32_e32 v99, v87
	v_pk_fma_f32 v[60:61], v[96:97], v[96:97], v[60:61]
	v_pk_fma_f32 v[56:57], v[90:91], v[90:91], v[56:57]
	v_pk_fma_f32 v[60:61], v[98:99], v[98:99], v[60:61]
	v_add_f32_e32 v56, v56, v57
	v_add_f32_e32 v56, v56, v60
	v_add_f32_e32 v56, v56, v61
	v_mov_b32_e32 v57, v56
	v_mov_b32_e32 v160, v56
	s_nop 1
	v_permlane32_swap_b32_e32 v57, v160
	s_waitcnt lgkmcnt(0)
	v_add_f32_e32 v56, v57, v160
	v_mov_b32_e32 v57, v56
	v_mov_b32_e32 v160, v56
	s_nop 1
	v_permlane16_swap_b32_e32 v57, v160
	s_waitcnt lgkmcnt(0)
	v_add_f32_e32 v56, v57, v160
	s_nop 1
	v_mov_b32_dpp v57, v56 row_ror:8 row_mask:0xf bank_mask:0xf
	s_waitcnt lgkmcnt(0)
	v_add_f32_e32 v56, v56, v57
	s_nop 1
	v_mov_b32_dpp v57, v56 row_ror:4 row_mask:0xf bank_mask:0xf
	s_waitcnt lgkmcnt(0)
	v_add_f32_e32 v56, v56, v57
	s_nop 1
	v_mov_b32_dpp v57, v56 row_ror:2 row_mask:0xf bank_mask:0xf
	s_waitcnt lgkmcnt(0)
	v_add_f32_e32 v60, v56, v57
	s_nop 1
	v_mov_b32_dpp v61, v60 row_ror:1 row_mask:0xf bank_mask:0xf
	v_lshlrev_b64 v[56:57], 11, v[58:59]
	s_waitcnt lgkmcnt(0)
	v_add_f32_e32 v58, v60, v61
	v_fmamk_f32 v58, v58, 0x3a800000, v70
	v_mul_f32_e32 v59, 0x4b800000, v58
	v_cmp_gt_f32_e32 vcc, s10, v58
	v_lshl_add_u64 v[60:61], v[34:35], 0, v[56:57]
	s_nop 0
	v_cndmask_b32_e32 v58, v58, v59, vcc
	v_rsq_f32_e32 v58, v58
	s_nop 0
	v_mul_f32_e32 v56, 0x45800000, v58
	v_cndmask_b32_e32 v56, v58, v56, vcc
	v_pk_mul_f32 v[58:59], v[74:75], v[56:57] op_sel_hi:[1,0]
	v_pk_mul_f32 v[72:73], v[72:73], v[56:57] op_sel_hi:[1,0]
	v_pk_mul_f32 v[74:75], v[78:79], v[56:57] op_sel_hi:[1,0]
	v_pk_mul_f32 v[76:77], v[76:77], v[56:57] op_sel_hi:[1,0]
	v_pk_mul_f32 v[78:79], v[82:83], v[56:57] op_sel_hi:[1,0]
	v_pk_mul_f32 v[80:81], v[80:81], v[56:57] op_sel_hi:[1,0]
	v_pk_mul_f32 v[82:83], v[86:87], v[56:57] op_sel_hi:[1,0]
	v_pk_mul_f32 v[56:57], v[84:85], v[56:57] op_sel_hi:[1,0]
	v_pk_mul_f32 v[72:73], v[4:5], v[72:73]
	v_pk_mul_f32 v[58:59], v[6:7], v[58:59]
	v_pk_mul_f32 v[76:77], v[0:1], v[76:77]
	v_pk_mul_f32 v[74:75], v[2:3], v[74:75]
	v_pk_mul_f32 v[80:81], v[20:21], v[80:81]
	v_pk_mul_f32 v[78:79], v[22:23], v[78:79]
	v_pk_mul_f32 v[56:57], v[16:17], v[56:57]
	v_pk_mul_f32 v[82:83], v[18:19], v[82:83]
	v_pk_fma_f32 v[58:59], v[40:41], v[58:59], v[14:15]
	v_pk_fma_f32 v[72:73], v[42:43], v[72:73], v[12:13]
	v_pk_fma_f32 v[74:75], v[44:45], v[74:75], v[10:11]
	v_pk_fma_f32 v[76:77], v[46:47], v[76:77], v[8:9]
	v_pk_fma_f32 v[78:79], v[48:49], v[78:79], v[30:31]
	v_pk_fma_f32 v[80:81], v[50:51], v[80:81], v[28:29]
	v_pk_fma_f32 v[82:83], v[52:53], v[82:83], v[26:27]
	v_pk_fma_f32 v[84:85], v[54:55], v[56:57], v[24:25]
	v_cvt_pk_bf16_f32 v56, v72, v73
	v_cvt_pk_bf16_f32 v57, v58, v59
	v_cvt_pk_bf16_f32 v58, v76, v77
	v_cvt_pk_bf16_f32 v59, v74, v75
	v_cvt_pk_bf16_f32 v72, v80, v81
	v_cvt_pk_bf16_f32 v73, v78, v79
	v_cvt_pk_bf16_f32 v74, v84, v85
	v_cvt_pk_bf16_f32 v75, v82, v83
	global_store_dwordx4 v[60:61], v[56:59], off sc1
	global_store_dwordx4 v[60:61], v[72:75], off offset:1024 sc1
	s_cbranch_scc1 .LBB0_113

.Lr0pfA_d:
	s_nop 0
	v_mov_b32_e32 v60, v73
	s_nop 0
	v_mov_b32_e32 v61, v77
	v_mov_b32_e32 v58, v72
	v_mov_b32_e32 v59, v76
	s_nop 0
	v_mov_b32_e32 v94, v81
	s_nop 0
	v_mov_b32_e32 v95, v85
	v_pk_mul_f32 v[60:61], v[60:61], v[60:61]
	v_mov_b32_e32 v88, v74
	v_mov_b32_e32 v89, v78
	v_mov_b32_e32 v92, v80
	v_mov_b32_e32 v93, v84
	v_pk_mul_f32 v[94:95], v[94:95], v[94:95]
	v_pk_fma_f32 v[58:59], v[58:59], v[58:59], v[60:61]
	v_mov_b32_e32 v90, v75
	v_mov_b32_e32 v91, v79
	v_mov_b32_e32 v96, v82
	v_mov_b32_e32 v97, v86
	v_pk_fma_f32 v[60:61], v[92:93], v[92:93], v[94:95]
	v_pk_fma_f32 v[58:59], v[88:89], v[88:89], v[58:59]
	v_mov_b32_e32 v98, v83
	v_mov_b32_e32 v99, v87
	v_pk_fma_f32 v[60:61], v[96:97], v[96:97], v[60:61]
	v_pk_fma_f32 v[58:59], v[90:91], v[90:91], v[58:59]
	v_pk_fma_f32 v[60:61], v[98:99], v[98:99], v[60:61]
	v_add_f32_e32 v58, v58, v59
	v_add_f32_e32 v58, v58, v60
	v_add_f32_e32 v58, v58, v61
	v_mov_b32_e32 v59, v58
	v_mov_b32_e32 v160, v58
	s_nop 1
	v_permlane32_swap_b32_e32 v59, v160
	v_lshlrev_b64 v[60:61], 11, v[56:57]
	v_lshl_add_u64 v[60:61], v[34:35], 0, v[60:61]
	s_waitcnt lgkmcnt(0)
	v_add_f32_e32 v58, v59, v160
	v_mov_b32_e32 v59, v58
	v_mov_b32_e32 v160, v58
	s_nop 1
	v_permlane16_swap_b32_e32 v59, v160
	s_waitcnt lgkmcnt(0)
	v_add_f32_e32 v58, v59, v160
	s_nop 1
	v_mov_b32_dpp v59, v58 row_ror:8 row_mask:0xf bank_mask:0xf
	s_waitcnt lgkmcnt(0)
	v_add_f32_e32 v58, v58, v59
	s_nop 1
	v_mov_b32_dpp v59, v58 row_ror:4 row_mask:0xf bank_mask:0xf
	s_waitcnt lgkmcnt(0)
	v_add_f32_e32 v58, v58, v59
	s_nop 1
	v_mov_b32_dpp v59, v58 row_ror:2 row_mask:0xf bank_mask:0xf
	s_waitcnt lgkmcnt(0)
	v_add_f32_e32 v58, v58, v59
	s_nop 1
	v_mov_b32_dpp v59, v58 row_ror:1 row_mask:0xf bank_mask:0xf
	s_waitcnt lgkmcnt(0)
	v_add_f32_e32 v58, v58, v59
	v_fmamk_f32 v58, v58, 0x3a800000, v70
	v_mul_f32_e32 v59, 0x4b800000, v58
	v_cmp_gt_f32_e32 vcc, s10, v58
	s_nop 1
	v_cndmask_b32_e32 v58, v58, v59, vcc
	v_rsq_f32_e32 v59, v58
	v_add_u32_e32 v58, 1, v56
	v_mul_f32_e32 v57, 0x45800000, v59
	v_cndmask_b32_e32 v88, v59, v57, vcc
	v_pk_mul_f32 v[74:75], v[74:75], v[88:89] op_sel_hi:[1,0]
	v_pk_mul_f32 v[72:73], v[72:73], v[88:89] op_sel_hi:[1,0]
	v_pk_mul_f32 v[78:79], v[78:79], v[88:89] op_sel_hi:[1,0]
	v_pk_mul_f32 v[76:77], v[76:77], v[88:89] op_sel_hi:[1,0]
	v_pk_mul_f32 v[82:83], v[82:83], v[88:89] op_sel_hi:[1,0]
	v_pk_mul_f32 v[80:81], v[80:81], v[88:89] op_sel_hi:[1,0]
	v_pk_mul_f32 v[86:87], v[86:87], v[88:89] op_sel_hi:[1,0]
	v_pk_mul_f32 v[84:85], v[84:85], v[88:89] op_sel_hi:[1,0]
	v_pk_mul_f32 v[72:73], v[4:5], v[72:73]
	v_pk_mul_f32 v[74:75], v[6:7], v[74:75]
	v_pk_mul_f32 v[76:77], v[0:1], v[76:77]
	v_pk_mul_f32 v[78:79], v[2:3], v[78:79]
	v_pk_mul_f32 v[80:81], v[20:21], v[80:81]
	v_pk_mul_f32 v[82:83], v[22:23], v[82:83]
	v_pk_mul_f32 v[84:85], v[16:17], v[84:85]
	v_pk_mul_f32 v[86:87], v[18:19], v[86:87]
	v_pk_fma_f32 v[74:75], v[40:41], v[74:75], v[14:15]
	v_pk_fma_f32 v[72:73], v[42:43], v[72:73], v[12:13]
	v_pk_fma_f32 v[78:79], v[44:45], v[78:79], v[10:11]
	v_pk_fma_f32 v[76:77], v[46:47], v[76:77], v[8:9]
	v_pk_fma_f32 v[82:83], v[48:49], v[82:83], v[30:31]
	v_pk_fma_f32 v[80:81], v[50:51], v[80:81], v[28:29]
	v_pk_fma_f32 v[86:87], v[52:53], v[86:87], v[26:27]
	v_pk_fma_f32 v[84:85], v[54:55], v[84:85], v[24:25]
	v_cvt_pk_bf16_f32 v72, v72, v73
	v_cvt_pk_bf16_f32 v73, v74, v75
	v_cvt_pk_bf16_f32 v74, v76, v77
	v_cvt_pk_bf16_f32 v75, v78, v79
	v_cmp_lt_i32_e32 vcc, s3, v58
	v_cvt_pk_bf16_f32 v76, v80, v81
	v_cvt_pk_bf16_f32 v77, v82, v83
	v_cvt_pk_bf16_f32 v78, v84, v85
	v_cvt_pk_bf16_f32 v79, v86, v87
	global_store_dwordx4 v[60:61], v[72:75], off sc1
	global_store_dwordx4 v[60:61], v[76:79], off offset:1024 sc1
	s_and_saveexec_b64 s[12:13], vcc
	s_xor_b64 s[12:13], exec, s[12:13]
	v_add_u32_e32 v56, 0xfffff001, v56
	v_mov_b32_e32 v57, v33
	v_lshlrev_b64 v[56:57], 12, v[56:57]
	v_lshl_add_u64 v[60:61], s[38:39], 0, v[56:57]
	v_mov_b32_e32 v59, v33
	s_andn2_saveexec_b64 s[12:13], s[12:13]
	s_cbranch_execz .LBB0_115
	v_ashrrev_i32_e32 v59, 31, v58
	v_lshlrev_b64 v[56:57], 12, v[58:59]
	v_lshl_add_u64 v[60:61], s[36:37], 0, v[56:57]
	s_branch .LBB0_115

.LBB0_568:
	s_or_b64 exec, exec, s[40:41]
	v_lshlrev_b64 v[98:99], 11, v[102:103]
	v_lshl_add_u64 v[102:103], v[66:67], 0, v[98:99]
	global_load_dwordx4 v[108:111], v[102:103], off
	global_load_dwordx4 v[112:115], v[102:103], off offset:1024
	v_lshl_add_u64 v[124:125], v[100:101], 0, v[64:65]
	global_load_dwordx4 v[100:103], v[124:125], off offset:16 nt
	global_load_dwordx4 v[116:119], v[124:125], off nt
	global_load_dwordx4 v[120:123], v[124:125], off offset:2064 nt
	s_nop 0
	global_load_dwordx4 v[124:127], v[124:125], off offset:2048 nt
	s_add_i32 s10, s10, 2
	s_cmp_eq_u32 s10, 4
	s_waitcnt vmcnt(5)
	v_and_b32_e32 v131, 0xffff0000, v110
	v_and_b32_e32 v130, 0xffff0000, v108
	v_lshlrev_b32_e32 v129, 16, v110
	v_lshlrev_b32_e32 v128, 16, v108
	v_lshlrev_b32_e32 v132, 16, v109
	v_and_b32_e32 v110, 0xffff0000, v109
	s_waitcnt vmcnt(4)
	v_lshlrev_b32_e32 v109, 16, v112
	v_lshlrev_b32_e32 v108, 16, v114
	v_and_b32_e32 v135, 0xffff0000, v112
	v_and_b32_e32 v134, 0xffff0000, v114
	v_lshlrev_b32_e32 v136, 16, v115
	v_and_b32_e32 v112, 0xffff0000, v115
	v_pk_mul_f32 v[114:115], v[130:131], v[130:131]
	v_lshlrev_b32_e32 v133, 16, v111
	v_pk_mul_f32 v[138:139], v[134:135], v[134:135]
	v_pk_fma_f32 v[114:115], v[128:129], v[128:129], v[114:115]
	v_and_b32_e32 v111, 0xffff0000, v111
	v_lshlrev_b32_e32 v137, 16, v113
	v_pk_fma_f32 v[138:139], v[108:109], v[108:109], v[138:139]
	v_pk_fma_f32 v[114:115], v[132:133], v[132:133], v[114:115]
	v_and_b32_e32 v113, 0xffff0000, v113
	v_pk_fma_f32 v[138:139], v[136:137], v[136:137], v[138:139]
	v_pk_fma_f32 v[114:115], v[110:111], v[110:111], v[114:115]
	v_pk_fma_f32 v[138:139], v[112:113], v[112:113], v[138:139]
	v_add_f32_e32 v114, v114, v115
	v_add_f32_e32 v114, v114, v139
	v_add_f32_e32 v114, v138, v114
	v_mov_b32_e32 v115, v114
	v_mov_b32_e32 v160, v114
	s_nop 1
	v_permlane32_swap_b32_e32 v115, v160
	v_mov_b32_e32 v139, v130
	v_mov_b32_e32 v130, v129
	v_mov_b32_e32 v129, v113
	v_mov_b32_e32 v141, v135
	s_waitcnt lgkmcnt(0)
	v_add_f32_e32 v114, v115, v160
	v_mov_b32_e32 v115, v114
	v_mov_b32_e32 v160, v114
	s_nop 1
	v_permlane16_swap_b32_e32 v115, v160
	s_waitcnt lgkmcnt(0)
	v_add_f32_e32 v114, v115, v160
	s_nop 1
	v_mov_b32_dpp v115, v114 row_ror:8 row_mask:0xf bank_mask:0xf
	s_waitcnt lgkmcnt(0)
	v_add_f32_e32 v115, v114, v115
	s_nop 1
	v_mov_b32_dpp v138, v115 row_ror:4 row_mask:0xf bank_mask:0xf
	v_mov_b32_e32 v114, v132
	s_waitcnt lgkmcnt(0)
	v_add_f32_e32 v132, v115, v138
	s_nop 1
	v_mov_b32_dpp v140, v132 row_ror:2 row_mask:0xf bank_mask:0xf
	v_mov_b32_e32 v115, v110
	v_mov_b32_e32 v138, v128
	v_mov_b32_e32 v128, v137
	v_mov_b32_e32 v137, v112
	s_waitcnt lgkmcnt(0)
	v_add_f32_e32 v110, v132, v140
	s_nop 1
	v_mov_b32_dpp v132, v110 row_ror:1 row_mask:0xf bank_mask:0xf
	v_mov_b32_e32 v140, v109
	s_waitcnt lgkmcnt(0)
	v_add_f32_e32 v109, v110, v132
	v_fmamk_f32 v109, v109, 0x3a800000, v106
	v_mul_f32_e32 v110, 0x4b800000, v109
	v_cmp_gt_f32_e32 vcc, s8, v109
	s_nop 1
	v_cndmask_b32_e32 v109, v109, v110, vcc
	v_rsq_f32_e32 v113, v109
	v_mov_b32_e32 v109, v134
	v_mov_b32_e32 v110, v133
	v_mul_f32_e32 v112, 0x45800000, v113
	v_cndmask_b32_e32 v112, v113, v112, vcc
	v_pk_mul_f32 v[132:133], v[112:113], v[138:139] op_sel_hi:[0,1]
	v_pk_mul_f32 v[130:131], v[112:113], v[130:131] op_sel_hi:[0,1]
	v_pk_mul_f32 v[114:115], v[112:113], v[114:115] op_sel_hi:[0,1]
	v_pk_mul_f32 v[110:111], v[112:113], v[110:111] op_sel_hi:[0,1]
	v_pk_mul_f32 v[128:129], v[112:113], v[128:129] op_sel_hi:[0,1]
	v_pk_mul_f32 v[134:135], v[112:113], v[140:141] op_sel_hi:[0,1]
	v_pk_mul_f32 v[136:137], v[112:113], v[136:137] op_sel_hi:[0,1]
	v_pk_mul_f32 v[108:109], v[112:113], v[108:109] op_sel_hi:[0,1]
	v_pk_mul_f32 v[112:113], v[4:5], v[132:133]
	v_pk_mul_f32 v[130:131], v[0:1], v[130:131]
	v_pk_mul_f32 v[132:133], v[36:37], v[134:135]
	v_pk_mul_f32 v[108:109], v[32:33], v[108:109]
	s_waitcnt vmcnt(2)
	v_pk_fma_f32 v[112:113], v[12:13], v[112:113], v[116:117]
	v_pk_fma_f32 v[116:117], v[8:9], v[130:131], v[100:101]
	v_pk_mul_f32 v[114:115], v[6:7], v[114:115]
	v_pk_mul_f32 v[110:111], v[2:3], v[110:111]
	s_waitcnt vmcnt(0)
	v_pk_fma_f32 v[124:125], v[44:45], v[132:133], v[124:125]
	v_pk_fma_f32 v[120:121], v[40:41], v[108:109], v[120:121]
	v_mov_b32_e32 v108, v113
	v_mov_b32_e32 v109, v117
	v_pk_mul_f32 v[128:129], v[38:39], v[128:129]
	v_pk_mul_f32 v[134:135], v[34:35], v[136:137]
	v_pk_fma_f32 v[114:115], v[14:15], v[114:115], v[118:119]
	v_pk_fma_f32 v[102:103], v[10:11], v[110:111], v[102:103]
	v_mov_b32_e32 v100, v112
	v_mov_b32_e32 v101, v116
	v_mov_b32_e32 v130, v121
	v_mov_b32_e32 v131, v125
	v_pk_mul_f32 v[108:109], v[108:109], v[108:109]
	v_pk_fma_f32 v[118:119], v[46:47], v[128:129], v[126:127]
	v_pk_fma_f32 v[122:123], v[42:43], v[134:135], v[122:123]
	v_mov_b32_e32 v110, v114
	v_mov_b32_e32 v111, v102
	v_mov_b32_e32 v128, v120
	v_mov_b32_e32 v129, v124
	v_pk_mul_f32 v[130:131], v[130:131], v[130:131]
	v_pk_fma_f32 v[100:101], v[100:101], v[100:101], v[108:109]
	v_mov_b32_e32 v126, v115
	v_mov_b32_e32 v127, v103
	v_mov_b32_e32 v132, v122
	v_mov_b32_e32 v133, v118
	v_pk_fma_f32 v[108:109], v[128:129], v[128:129], v[130:131]
	v_pk_fma_f32 v[100:101], v[110:111], v[110:111], v[100:101]
	v_mov_b32_e32 v134, v123
	v_mov_b32_e32 v135, v119
	v_pk_fma_f32 v[108:109], v[132:133], v[132:133], v[108:109]
	v_pk_fma_f32 v[100:101], v[126:127], v[126:127], v[100:101]
	v_pk_fma_f32 v[108:109], v[134:135], v[134:135], v[108:109]
	v_add_f32_e32 v100, v100, v101
	v_add_f32_e32 v100, v109, v100
	v_add_f32_e32 v100, v108, v100
	v_mov_b32_e32 v101, v100
	v_mov_b32_e32 v160, v100
	s_nop 1
	v_permlane32_swap_b32_e32 v101, v160
	v_lshl_add_u64 v[126:127], v[68:69], 0, v[98:99]
	v_lshl_add_u64 v[128:129], v[70:71], 0, v[98:99]
	v_cvt_pk_bf16_f32 v98, v112, v113
	v_cvt_pk_bf16_f32 v99, v114, v115
	s_waitcnt lgkmcnt(0)
	v_add_f32_e32 v100, v101, v160
	v_mov_b32_e32 v101, v100
	v_mov_b32_e32 v160, v100
	s_nop 1
	v_permlane16_swap_b32_e32 v101, v160
	v_cvt_pk_bf16_f32 v109, v118, v119
	v_cvt_pk_bf16_f32 v110, v120, v121
	s_waitcnt lgkmcnt(0)
	v_add_f32_e32 v100, v101, v160
	s_nop 1
	v_mov_b32_dpp v101, v100 row_ror:8 row_mask:0xf bank_mask:0xf
	s_waitcnt lgkmcnt(0)
	v_add_f32_e32 v100, v100, v101
	s_nop 1
	v_mov_b32_dpp v101, v100 row_ror:4 row_mask:0xf bank_mask:0xf
	s_waitcnt lgkmcnt(0)
	v_add_f32_e32 v101, v100, v101
	s_nop 1
	v_mov_b32_dpp v108, v101 row_ror:2 row_mask:0xf bank_mask:0xf
	v_cvt_pk_bf16_f32 v100, v116, v117
	s_waitcnt lgkmcnt(0)
	v_add_f32_e32 v111, v101, v108
	s_nop 1
	v_mov_b32_dpp v130, v111 row_ror:1 row_mask:0xf bank_mask:0xf
	v_cvt_pk_bf16_f32 v101, v102, v103
	v_cvt_pk_bf16_f32 v108, v124, v125
	s_waitcnt lgkmcnt(0)
	v_add_f32_e32 v111, v111, v130
	v_fmamk_f32 v111, v111, 0x3a800000, v106
	v_mul_f32_e32 v130, 0x4b800000, v111
	v_cmp_gt_f32_e32 vcc, s8, v111
	s_nop 1
	v_cndmask_b32_e32 v111, v111, v130, vcc
	v_rsq_f32_e32 v130, v111
	v_cvt_pk_bf16_f32 v111, v122, v123
	global_store_dwordx4 v[126:127], v[98:101], off sc1
	global_store_dwordx4 v[126:127], v[108:111], off offset:1024 sc1
	s_nop 0
	v_mul_f32_e32 v98, 0x45800000, v130
	v_cndmask_b32_e32 v98, v130, v98, vcc
	v_pk_mul_f32 v[100:101], v[114:115], v[98:99] op_sel_hi:[1,0]
	v_pk_mul_f32 v[108:109], v[112:113], v[98:99] op_sel_hi:[1,0]
	v_pk_mul_f32 v[102:103], v[102:103], v[98:99] op_sel_hi:[1,0]
	v_pk_mul_f32 v[110:111], v[116:117], v[98:99] op_sel_hi:[1,0]
	v_pk_mul_f32 v[112:113], v[118:119], v[98:99] op_sel_hi:[1,0]
	v_pk_mul_f32 v[114:115], v[124:125], v[98:99] op_sel_hi:[1,0]
	v_pk_mul_f32 v[116:117], v[122:123], v[98:99] op_sel_hi:[1,0]
	v_pk_mul_f32 v[98:99], v[120:121], v[98:99] op_sel_hi:[1,0]
	v_pk_mul_f32 v[108:109], v[20:21], v[108:109]
	v_pk_mul_f32 v[100:101], v[22:23], v[100:101]
	v_pk_mul_f32 v[110:111], v[16:17], v[110:111]
	v_pk_mul_f32 v[102:103], v[18:19], v[102:103]
	v_pk_mul_f32 v[114:115], v[52:53], v[114:115]
	v_pk_mul_f32 v[112:113], v[54:55], v[112:113]
	v_pk_mul_f32 v[98:99], v[48:49], v[98:99]
	v_pk_mul_f32 v[116:117], v[50:51], v[116:117]
	v_pk_fma_f32 v[100:101], v[82:83], v[100:101], v[30:31]
	v_pk_fma_f32 v[108:109], v[84:85], v[108:109], v[28:29]
	v_pk_fma_f32 v[102:103], v[86:87], v[102:103], v[26:27]
	v_pk_fma_f32 v[110:111], v[88:89], v[110:111], v[24:25]
	v_pk_fma_f32 v[112:113], v[90:91], v[112:113], v[62:63]
	v_pk_fma_f32 v[114:115], v[92:93], v[114:115], v[60:61]
	v_pk_fma_f32 v[116:117], v[94:95], v[116:117], v[58:59]
	v_pk_fma_f32 v[118:119], v[96:97], v[98:99], v[56:57]
	v_cvt_pk_bf16_f32 v98, v108, v109
	v_cvt_pk_bf16_f32 v99, v100, v101
	v_cvt_pk_bf16_f32 v100, v110, v111
	v_cvt_pk_bf16_f32 v101, v102, v103
	v_cvt_pk_bf16_f32 v108, v114, v115
	v_cvt_pk_bf16_f32 v109, v112, v113
	v_cvt_pk_bf16_f32 v110, v118, v119
	v_cvt_pk_bf16_f32 v111, v116, v117
	global_store_dwordx4 v[128:129], v[98:101], off sc1
	global_store_dwordx4 v[128:129], v[108:111], off offset:1024 sc1
	s_cbranch_scc1 .LBB0_566
.LBB0_569:
	v_add_u32_e32 v98, s10, v104
	v_cmp_lt_i32_e32 vcc, s3, v98
	s_and_saveexec_b64 s[16:17], vcc
	s_xor_b64 s[40:41], exec, s[16:17]
	v_add_u32_e32 v100, 0xfffff000, v98
	v_mov_b32_e32 v101, v65
	v_lshlrev_b64 v[100:101], 12, v[100:101]
	v_lshl_add_u64 v[102:103], s[38:39], 0, v[100:101]
	v_mov_b32_e32 v99, v65
	s_andn2_saveexec_b64 s[40:41], s[40:41]
	v_ashrrev_i32_e32 v99, 31, v98
	v_lshlrev_b64 v[100:101], 12, v[98:99]
	v_lshl_add_u64 v[102:103], s[36:37], 0, v[100:101]
	s_or_b64 exec, exec, s[40:41]
	v_lshlrev_b64 v[100:101], 11, v[98:99]
	v_lshl_add_u64 v[112:113], v[66:67], 0, v[100:101]
	global_load_dwordx4 v[108:111], v[112:113], off
	s_nop 0
	global_load_dwordx4 v[112:115], v[112:113], off offset:1024
	v_lshl_add_u64 v[102:103], v[102:103], 0, v[64:65]
	global_load_dwordx4 v[116:119], v[102:103], off offset:16 nt
	global_load_dwordx4 v[120:123], v[102:103], off nt
	global_load_dwordx4 v[124:127], v[102:103], off offset:2064 nt
	global_load_dwordx4 v[128:131], v[102:103], off offset:2048 nt
	s_waitcnt vmcnt(5)
	v_and_b32_e32 v133, 0xffff0000, v110
	v_and_b32_e32 v132, 0xffff0000, v108
	v_lshlrev_b32_e32 v103, 16, v110
	v_lshlrev_b32_e32 v102, 16, v108
	v_lshlrev_b32_e32 v134, 16, v109
	v_and_b32_e32 v110, 0xffff0000, v109
	s_waitcnt vmcnt(4)
	v_lshlrev_b32_e32 v109, 16, v112
	v_lshlrev_b32_e32 v108, 16, v114
	v_and_b32_e32 v137, 0xffff0000, v112
	v_and_b32_e32 v136, 0xffff0000, v114
	v_lshlrev_b32_e32 v138, 16, v115
	v_and_b32_e32 v112, 0xffff0000, v115
	v_pk_mul_f32 v[114:115], v[132:133], v[132:133]
	v_lshlrev_b32_e32 v135, 16, v111
	v_pk_mul_f32 v[140:141], v[136:137], v[136:137]
	v_pk_fma_f32 v[114:115], v[102:103], v[102:103], v[114:115]
	v_and_b32_e32 v111, 0xffff0000, v111
	v_lshlrev_b32_e32 v139, 16, v113
	v_pk_fma_f32 v[140:141], v[108:109], v[108:109], v[140:141]
	v_pk_fma_f32 v[114:115], v[134:135], v[134:135], v[114:115]
	v_and_b32_e32 v113, 0xffff0000, v113
	v_pk_fma_f32 v[140:141], v[138:139], v[138:139], v[140:141]
	v_pk_fma_f32 v[114:115], v[110:111], v[110:111], v[114:115]
	v_pk_fma_f32 v[140:141], v[112:113], v[112:113], v[140:141]
	v_add_f32_e32 v99, v114, v115
	v_add_f32_e32 v99, v99, v141
	v_add_f32_e32 v99, v140, v99
	v_mov_b32_e32 v114, v99
	v_mov_b32_e32 v160, v99
	s_nop 1
	v_permlane32_swap_b32_e32 v114, v160
	v_mov_b32_e32 v142, v109
	v_mov_b32_e32 v140, v102
	v_mov_b32_e32 v102, v139
	v_mov_b32_e32 v139, v112
	s_waitcnt lgkmcnt(0)
	v_add_f32_e32 v99, v114, v160
	v_mov_b32_e32 v114, v99
	v_mov_b32_e32 v160, v99
	s_nop 1
	v_permlane16_swap_b32_e32 v114, v160
	v_mov_b32_e32 v141, v132
	v_mov_b32_e32 v132, v103
	v_mov_b32_e32 v103, v113
	v_mov_b32_e32 v143, v137
	s_waitcnt lgkmcnt(0)
	v_add_f32_e32 v99, v114, v160
	s_nop 1
	v_mov_b32_dpp v114, v99 row_ror:8 row_mask:0xf bank_mask:0xf
	s_waitcnt lgkmcnt(0)
	v_add_f32_e32 v99, v99, v114
	s_nop 1
	v_mov_b32_dpp v115, v99 row_ror:4 row_mask:0xf bank_mask:0xf
	v_mov_b32_e32 v114, v134
	s_waitcnt lgkmcnt(0)
	v_add_f32_e32 v99, v99, v115
	s_nop 1
	v_mov_b32_dpp v134, v99 row_ror:2 row_mask:0xf bank_mask:0xf
	v_mov_b32_e32 v115, v110
	s_waitcnt lgkmcnt(0)
	v_add_f32_e32 v99, v99, v134
	s_nop 1
	v_mov_b32_dpp v110, v99 row_ror:1 row_mask:0xf bank_mask:0xf
	s_waitcnt lgkmcnt(0)
	v_add_f32_e32 v99, v99, v110
	v_fmamk_f32 v99, v99, 0x3a800000, v106
	v_mul_f32_e32 v109, 0x4b800000, v99
	v_cmp_gt_f32_e32 vcc, s8, v99
	v_mov_b32_e32 v110, v135
	s_nop 0
	v_cndmask_b32_e32 v99, v99, v109, vcc
	v_rsq_f32_e32 v99, v99
	v_mov_b32_e32 v109, v136
	v_mul_f32_e32 v112, 0x45800000, v99
	v_cndmask_b32_e32 v112, v99, v112, vcc
	v_pk_mul_f32 v[134:135], v[112:113], v[140:141] op_sel_hi:[0,1]
	v_pk_mul_f32 v[132:133], v[112:113], v[132:133] op_sel_hi:[0,1]
	v_pk_mul_f32 v[114:115], v[112:113], v[114:115] op_sel_hi:[0,1]
	v_pk_mul_f32 v[110:111], v[112:113], v[110:111] op_sel_hi:[0,1]
	v_pk_mul_f32 v[102:103], v[112:113], v[102:103] op_sel_hi:[0,1]
	v_pk_mul_f32 v[136:137], v[112:113], v[142:143] op_sel_hi:[0,1]
	v_pk_mul_f32 v[138:139], v[112:113], v[138:139] op_sel_hi:[0,1]
	v_pk_mul_f32 v[108:109], v[112:113], v[108:109] op_sel_hi:[0,1]
	v_pk_mul_f32 v[112:113], v[4:5], v[134:135]
	v_pk_mul_f32 v[132:133], v[0:1], v[132:133]
	v_pk_mul_f32 v[134:135], v[36:37], v[136:137]
	v_pk_mul_f32 v[108:109], v[32:33], v[108:109]
	s_waitcnt vmcnt(2)
	v_pk_fma_f32 v[120:121], v[12:13], v[112:113], v[120:121]
	v_pk_fma_f32 v[116:117], v[8:9], v[132:133], v[116:117]
	v_pk_mul_f32 v[114:115], v[6:7], v[114:115]
	v_pk_mul_f32 v[110:111], v[2:3], v[110:111]
	v_pk_mul_f32 v[102:103], v[38:39], v[102:103]
	s_waitcnt vmcnt(0)
	v_pk_fma_f32 v[128:129], v[44:45], v[134:135], v[128:129]
	v_pk_fma_f32 v[124:125], v[40:41], v[108:109], v[124:125]
	v_mov_b32_e32 v108, v121
	v_mov_b32_e32 v109, v117
	v_pk_mul_f32 v[136:137], v[34:35], v[138:139]
	v_pk_fma_f32 v[122:123], v[14:15], v[114:115], v[122:123]
	v_pk_fma_f32 v[118:119], v[10:11], v[110:111], v[118:119]
	v_pk_fma_f32 v[130:131], v[46:47], v[102:103], v[130:131]
	v_mov_b32_e32 v102, v120
	v_mov_b32_e32 v103, v116
	v_mov_b32_e32 v132, v125
	v_mov_b32_e32 v133, v129
	v_pk_mul_f32 v[108:109], v[108:109], v[108:109]
	v_pk_fma_f32 v[126:127], v[42:43], v[136:137], v[126:127]
	v_mov_b32_e32 v110, v122
	v_mov_b32_e32 v111, v118
	v_mov_b32_e32 v114, v124
	v_mov_b32_e32 v115, v128
	v_pk_mul_f32 v[132:133], v[132:133], v[132:133]
	v_pk_fma_f32 v[102:103], v[102:103], v[102:103], v[108:109]
	v_mov_b32_e32 v112, v123
	v_mov_b32_e32 v113, v119
	v_mov_b32_e32 v134, v126
	v_mov_b32_e32 v135, v130
	v_pk_fma_f32 v[108:109], v[114:115], v[114:115], v[132:133]
	v_pk_fma_f32 v[102:103], v[110:111], v[110:111], v[102:103]
	v_mov_b32_e32 v136, v127
	v_mov_b32_e32 v137, v131
	v_pk_fma_f32 v[108:109], v[134:135], v[134:135], v[108:109]
	v_pk_fma_f32 v[102:103], v[112:113], v[112:113], v[102:103]
	v_pk_fma_f32 v[108:109], v[136:137], v[136:137], v[108:109]
	v_add_f32_e32 v99, v102, v103
	v_add_f32_e32 v99, v109, v99
	v_add_f32_e32 v99, v108, v99
	v_mov_b32_e32 v102, v99
	v_mov_b32_e32 v160, v99
	s_nop 1
	v_permlane32_swap_b32_e32 v102, v160
	v_lshl_add_u64 v[132:133], v[68:69], 0, v[100:101]
	v_cvt_pk_bf16_f32 v108, v120, v121
	v_cvt_pk_bf16_f32 v109, v122, v123
	v_cvt_pk_bf16_f32 v110, v116, v117
	s_waitcnt lgkmcnt(0)
	v_add_f32_e32 v99, v102, v160
	v_mov_b32_e32 v102, v99
	v_mov_b32_e32 v160, v99
	s_nop 1
	v_permlane16_swap_b32_e32 v102, v160
	v_cvt_pk_bf16_f32 v111, v118, v119
	v_cvt_pk_bf16_f32 v112, v128, v129
	v_cvt_pk_bf16_f32 v113, v130, v131
	v_cvt_pk_bf16_f32 v114, v124, v125
	s_waitcnt lgkmcnt(0)
	v_add_f32_e32 v99, v102, v160
	s_nop 1
	v_mov_b32_dpp v102, v99 row_ror:8 row_mask:0xf bank_mask:0xf
	v_cvt_pk_bf16_f32 v115, v126, v127
	global_store_dwordx4 v[132:133], v[108:111], off sc1
	global_store_dwordx4 v[132:133], v[112:115], off offset:1024 sc1
	v_lshl_add_u64 v[100:101], v[70:71], 0, v[100:101]
	s_waitcnt lgkmcnt(0)
	v_add_f32_e32 v99, v99, v102
	s_nop 1
	v_mov_b32_dpp v103, v99 row_ror:4 row_mask:0xf bank_mask:0xf
	v_add_u32_e32 v102, 1, v98
	s_waitcnt lgkmcnt(0)
	v_add_f32_e32 v99, v99, v103
	s_nop 1
	v_mov_b32_dpp v103, v99 row_ror:2 row_mask:0xf bank_mask:0xf
	s_waitcnt lgkmcnt(0)
	v_add_f32_e32 v99, v99, v103
	s_nop 1
	v_mov_b32_dpp v103, v99 row_ror:1 row_mask:0xf bank_mask:0xf
	s_waitcnt lgkmcnt(0)
	v_add_f32_e32 v99, v99, v103
	v_fmamk_f32 v99, v99, 0x3a800000, v106
	v_mul_f32_e32 v103, 0x4b800000, v99
	v_cmp_gt_f32_e32 vcc, s8, v99
	s_nop 1
	v_cndmask_b32_e32 v99, v99, v103, vcc
	v_rsq_f32_e32 v99, v99
	s_nop 0
	v_mul_f32_e32 v103, 0x45800000, v99
	v_cndmask_b32_e32 v108, v99, v103, vcc
	v_pk_mul_f32 v[110:111], v[122:123], v[108:109] op_sel_hi:[1,0]
	v_pk_mul_f32 v[112:113], v[120:121], v[108:109] op_sel_hi:[1,0]
	v_pk_mul_f32 v[114:115], v[118:119], v[108:109] op_sel_hi:[1,0]
	v_pk_mul_f32 v[116:117], v[116:117], v[108:109] op_sel_hi:[1,0]
	v_pk_mul_f32 v[118:119], v[130:131], v[108:109] op_sel_hi:[1,0]
	v_pk_mul_f32 v[120:121], v[128:129], v[108:109] op_sel_hi:[1,0]
	v_pk_mul_f32 v[122:123], v[126:127], v[108:109] op_sel_hi:[1,0]
	v_pk_mul_f32 v[108:109], v[124:125], v[108:109] op_sel_hi:[1,0]
	v_pk_mul_f32 v[112:113], v[20:21], v[112:113]
	v_pk_mul_f32 v[110:111], v[22:23], v[110:111]
	v_pk_mul_f32 v[116:117], v[16:17], v[116:117]
	v_pk_mul_f32 v[114:115], v[18:19], v[114:115]
	v_pk_mul_f32 v[120:121], v[52:53], v[120:121]
	v_pk_mul_f32 v[118:119], v[54:55], v[118:119]
	v_pk_mul_f32 v[108:109], v[48:49], v[108:109]
	v_pk_mul_f32 v[122:123], v[50:51], v[122:123]
	v_pk_fma_f32 v[110:111], v[82:83], v[110:111], v[30:31]
	v_pk_fma_f32 v[112:113], v[84:85], v[112:113], v[28:29]
	v_pk_fma_f32 v[114:115], v[86:87], v[114:115], v[26:27]
	v_pk_fma_f32 v[116:117], v[88:89], v[116:117], v[24:25]
	v_pk_fma_f32 v[118:119], v[90:91], v[118:119], v[62:63]
	v_pk_fma_f32 v[120:121], v[92:93], v[120:121], v[60:61]
	v_pk_fma_f32 v[122:123], v[94:95], v[122:123], v[58:59]
	v_pk_fma_f32 v[124:125], v[96:97], v[108:109], v[56:57]
	v_cvt_pk_bf16_f32 v108, v112, v113
	v_cvt_pk_bf16_f32 v109, v110, v111
	v_cvt_pk_bf16_f32 v110, v116, v117
	v_cvt_pk_bf16_f32 v111, v114, v115
	v_cmp_lt_i32_e32 vcc, s3, v102
	v_cvt_pk_bf16_f32 v112, v120, v121
	v_cvt_pk_bf16_f32 v113, v118, v119
	v_cvt_pk_bf16_f32 v114, v124, v125
	v_cvt_pk_bf16_f32 v115, v122, v123
	global_store_dwordx4 v[100:101], v[108:111], off sc1
	global_store_dwordx4 v[100:101], v[112:115], off offset:1024 sc1
	s_and_saveexec_b64 s[16:17], vcc
	s_xor_b64 s[40:41], exec, s[16:17]
	v_add_u32_e32 v98, 0xfffff001, v98
	v_mov_b32_e32 v99, v65
	v_lshlrev_b64 v[98:99], 12, v[98:99]
	v_lshl_add_u64 v[100:101], s[38:39], 0, v[98:99]
	v_mov_b32_e32 v103, v65
	s_andn2_saveexec_b64 s[40:41], s[40:41]
	s_cbranch_execz .LBB0_568
	v_ashrrev_i32_e32 v103, 31, v102
	v_lshlrev_b64 v[98:99], 12, v[102:103]
	v_lshl_add_u64 v[100:101], s[36:37], 0, v[98:99]
	s_branch .LBB0_568

.Lrpfr20A_d:
	s_nop 0
	v_ashrrev_i32_e32 v101, 31, v100
	v_lshl_add_u64 v[124:125], v[70:71], 0, v[98:99]
	v_lshlrev_b64 v[98:99], 11, v[100:101]
	v_lshl_add_u64 v[100:101], v[66:67], 0, v[98:99]
	v_lshl_add_u64 v[126:127], v[68:69], 0, v[98:99]
	s_add_i32 s5, s5, 2
	s_cmp_eq_u32 s5, 4
	v_lshl_add_u64 v[98:99], v[70:71], 0, v[98:99]
	s_nop 0
	v_lshlrev_b32_e32 v128, 16, v106
	v_and_b32_e32 v129, 0xffff0000, v106
	s_nop 0
	v_and_b32_e32 v139, 0xffff0000, v116
	v_and_b32_e32 v138, 0xffff0000, v114
	v_lshlrev_b32_e32 v137, 16, v116
	v_lshlrev_b32_e32 v136, 16, v114
	v_lshlrev_b32_e32 v140, 16, v115
	v_and_b32_e32 v116, 0xffff0000, v115
	s_nop 0
	v_lshlrev_b32_e32 v115, 16, v118
	v_lshlrev_b32_e32 v114, 16, v120
	v_and_b32_e32 v143, 0xffff0000, v118
	v_and_b32_e32 v142, 0xffff0000, v120
	v_lshlrev_b32_e32 v150, 16, v121
	v_and_b32_e32 v118, 0xffff0000, v121
	v_pk_mul_f32 v[120:121], v[138:139], v[138:139]
	v_lshlrev_b32_e32 v141, 16, v117
	v_pk_mul_f32 v[152:153], v[142:143], v[142:143]
	v_pk_fma_f32 v[120:121], v[136:137], v[136:137], v[120:121]
	v_and_b32_e32 v117, 0xffff0000, v117
	v_lshlrev_b32_e32 v151, 16, v119
	v_mov_b32_e32 v156, v136
	v_mov_b32_e32 v157, v138
	v_mov_b32_e32 v138, v137
	v_pk_fma_f32 v[136:137], v[114:115], v[114:115], v[152:153]
	v_pk_fma_f32 v[120:121], v[140:141], v[140:141], v[120:121]
	v_and_b32_e32 v119, 0xffff0000, v119
	v_pk_fma_f32 v[136:137], v[150:151], v[150:151], v[136:137]
	v_pk_fma_f32 v[120:121], v[116:117], v[116:117], v[120:121]
	v_mov_b32_e32 v158, v151
	v_mov_b32_e32 v159, v119
	v_mov_b32_e32 v151, v118
	v_pk_fma_f32 v[118:119], v[118:119], v[118:119], v[136:137]
	v_add_f32_e32 v120, v120, v121
	v_add_f32_e32 v119, v120, v119
	v_add_f32_e32 v118, v118, v119
	v_mov_b32_e32 v119, v118
	v_mov_b32_e32 v160, v118
	s_nop 1
	v_permlane32_swap_b32_e32 v119, v160
	v_mov_b32_e32 v154, v140
	v_mov_b32_e32 v155, v116
	v_mov_b32_e32 v116, v141
	v_mov_b32_e32 v186, v115
	s_waitcnt lgkmcnt(0)
	v_add_f32_e32 v118, v119, v160
	v_mov_b32_e32 v119, v118
	v_mov_b32_e32 v160, v118
	s_nop 1
	v_permlane16_swap_b32_e32 v119, v160
	v_mov_b32_e32 v187, v143
	v_mov_b32_e32 v115, v142
	v_lshlrev_b32_e32 v106, 16, v107
	v_and_b32_e32 v107, 0xffff0000, v107
	s_waitcnt lgkmcnt(0)
	v_add_f32_e32 v118, v119, v160
	s_nop 1
	v_mov_b32_dpp v119, v118 row_ror:8 row_mask:0xf bank_mask:0xf
	v_lshlrev_b32_e32 v130, 16, v108
	v_and_b32_e32 v131, 0xffff0000, v108
	v_lshlrev_b32_e32 v108, 16, v109
	v_and_b32_e32 v109, 0xffff0000, v109
	s_waitcnt lgkmcnt(0)
	v_add_f32_e32 v118, v118, v119
	s_nop 1
	v_mov_b32_dpp v119, v118 row_ror:4 row_mask:0xf bank_mask:0xf
	v_lshlrev_b32_e32 v132, 16, v110
	v_and_b32_e32 v133, 0xffff0000, v110
	v_lshlrev_b32_e32 v110, 16, v111
	v_and_b32_e32 v111, 0xffff0000, v111
	s_waitcnt lgkmcnt(0)
	v_add_f32_e32 v118, v118, v119
	s_nop 1
	v_mov_b32_dpp v119, v118 row_ror:2 row_mask:0xf bank_mask:0xf
	v_lshlrev_b32_e32 v134, 16, v112
	v_and_b32_e32 v135, 0xffff0000, v112
	v_lshlrev_b32_e32 v112, 16, v113
	v_and_b32_e32 v113, 0xffff0000, v113
	s_waitcnt lgkmcnt(0)
	v_add_f32_e32 v118, v118, v119
	s_nop 1
	v_mov_b32_dpp v119, v118 row_ror:1 row_mask:0xf bank_mask:0xf
	s_waitcnt lgkmcnt(0)
	v_add_f32_e32 v118, v118, v119
	v_fmamk_f32 v118, v118, 0x3a800000, v104
	v_mul_f32_e32 v119, 0x4b800000, v118
	v_cmp_gt_f32_e32 vcc, s3, v118
	s_nop 1
	v_cndmask_b32_e32 v118, v118, v119, vcc
	v_rsq_f32_e32 v118, v118
	s_nop 0
	v_mul_f32_e32 v119, 0x45800000, v118
	v_cndmask_b32_e32 v118, v118, v119, vcc
	v_pk_mul_f32 v[120:121], v[118:119], v[154:155] op_sel_hi:[0,1]
	v_pk_mul_f32 v[136:137], v[118:119], v[156:157] op_sel_hi:[0,1]
	v_pk_mul_f32 v[116:117], v[118:119], v[116:117] op_sel_hi:[0,1]
	v_pk_mul_f32 v[138:139], v[118:119], v[138:139] op_sel_hi:[0,1]
	v_pk_mul_f32 v[140:141], v[118:119], v[158:159] op_sel_hi:[0,1]
	v_pk_mul_f32 v[142:143], v[118:119], v[186:187] op_sel_hi:[0,1]
	v_pk_mul_f32 v[150:151], v[118:119], v[150:151] op_sel_hi:[0,1]
	v_pk_mul_f32 v[114:115], v[118:119], v[114:115] op_sel_hi:[0,1]
	v_pk_mul_f32 v[118:119], v[4:5], v[136:137]
	v_pk_mul_f32 v[120:121], v[6:7], v[120:121]
	v_pk_mul_f32 v[136:137], v[0:1], v[138:139]
	v_pk_mul_f32 v[116:117], v[2:3], v[116:117]
	v_pk_mul_f32 v[138:139], v[36:37], v[142:143]
	v_pk_mul_f32 v[140:141], v[38:39], v[140:141]
	v_pk_mul_f32 v[114:115], v[32:33], v[114:115]
	v_pk_mul_f32 v[142:143], v[34:35], v[150:151]
	v_pk_fma_f32 v[120:121], v[14:15], v[120:121], v[106:107]
	v_pk_fma_f32 v[118:119], v[12:13], v[118:119], v[128:129]
	v_pk_fma_f32 v[116:117], v[10:11], v[116:117], v[108:109]
	v_pk_fma_f32 v[128:129], v[8:9], v[136:137], v[130:131]
	v_pk_fma_f32 v[130:131], v[46:47], v[140:141], v[110:111]
	v_pk_fma_f32 v[132:133], v[44:45], v[138:139], v[132:133]
	v_pk_fma_f32 v[136:137], v[42:43], v[142:143], v[112:113]
	v_pk_fma_f32 v[114:115], v[40:41], v[114:115], v[134:135]
	v_cvt_pk_bf16_f32 v106, v118, v119
	v_cvt_pk_bf16_f32 v107, v120, v121
	v_cvt_pk_bf16_f32 v108, v128, v129
	v_cvt_pk_bf16_f32 v109, v116, v117
	v_mov_b32_e32 v138, v119
	v_mov_b32_e32 v139, v129
	v_cvt_pk_bf16_f32 v110, v132, v133
	v_cvt_pk_bf16_f32 v111, v130, v131
	v_cvt_pk_bf16_f32 v112, v114, v115
	v_cvt_pk_bf16_f32 v113, v136, v137
	v_mov_b32_e32 v134, v118
	v_mov_b32_e32 v135, v128
	v_mov_b32_e32 v152, v115
	v_mov_b32_e32 v153, v133
	global_store_dwordx4 v[122:123], v[106:109], off sc1
	global_store_dwordx4 v[122:123], v[110:113], off offset:1024 sc1
	v_mov_b32_e32 v140, v120
	v_pk_mul_f32 v[106:107], v[138:139], v[138:139]
	v_mov_b32_e32 v141, v116
	v_mov_b32_e32 v150, v114
	v_mov_b32_e32 v151, v132
	v_pk_mul_f32 v[108:109], v[152:153], v[152:153]
	v_pk_fma_f32 v[106:107], v[134:135], v[134:135], v[106:107]
	v_mov_b32_e32 v142, v121
	v_mov_b32_e32 v143, v117
	v_mov_b32_e32 v154, v136
	v_mov_b32_e32 v155, v130
	v_pk_fma_f32 v[108:109], v[150:151], v[150:151], v[108:109]
	v_pk_fma_f32 v[106:107], v[140:141], v[140:141], v[106:107]
	v_mov_b32_e32 v156, v137
	v_mov_b32_e32 v157, v131
	v_pk_fma_f32 v[108:109], v[154:155], v[154:155], v[108:109]
	v_pk_fma_f32 v[106:107], v[142:143], v[142:143], v[106:107]
	v_pk_fma_f32 v[108:109], v[156:157], v[156:157], v[108:109]
	v_add_f32_e32 v106, v106, v107
	v_add_f32_e32 v106, v109, v106
	v_add_f32_e32 v106, v108, v106
	v_mov_b32_e32 v107, v106
	v_mov_b32_e32 v160, v106
	s_nop 1
	v_permlane32_swap_b32_e32 v107, v160
	s_waitcnt lgkmcnt(0)
	v_add_f32_e32 v106, v107, v160
	v_mov_b32_e32 v107, v106
	v_mov_b32_e32 v160, v106
	s_nop 1
	v_permlane16_swap_b32_e32 v107, v160
	s_waitcnt lgkmcnt(0)
	v_add_f32_e32 v106, v107, v160
	s_nop 1
	v_mov_b32_dpp v107, v106 row_ror:8 row_mask:0xf bank_mask:0xf
	s_waitcnt lgkmcnt(0)
	v_add_f32_e32 v106, v106, v107
	s_nop 1
	v_mov_b32_dpp v107, v106 row_ror:4 row_mask:0xf bank_mask:0xf
	s_waitcnt lgkmcnt(0)
	v_add_f32_e32 v106, v106, v107
	s_nop 1
	v_mov_b32_dpp v107, v106 row_ror:2 row_mask:0xf bank_mask:0xf
	s_waitcnt lgkmcnt(0)
	v_add_f32_e32 v106, v106, v107
	s_nop 1
	v_mov_b32_dpp v107, v106 row_ror:1 row_mask:0xf bank_mask:0xf
	s_waitcnt lgkmcnt(0)
	v_add_f32_e32 v106, v106, v107
	v_fmamk_f32 v106, v106, 0x3a800000, v104
	v_mul_f32_e32 v107, 0x4b800000, v106
	v_cmp_gt_f32_e32 vcc, s3, v106
	s_nop 1
	v_cndmask_b32_e32 v106, v106, v107, vcc
	v_rsq_f32_e32 v106, v106
	s_nop 0
	v_mul_f32_e32 v107, 0x45800000, v106
	v_cndmask_b32_e32 v106, v106, v107, vcc
	v_pk_mul_f32 v[108:109], v[120:121], v[106:107] op_sel_hi:[1,0]
	v_pk_mul_f32 v[110:111], v[118:119], v[106:107] op_sel_hi:[1,0]
	v_pk_mul_f32 v[112:113], v[116:117], v[106:107] op_sel_hi:[1,0]
	v_pk_mul_f32 v[116:117], v[128:129], v[106:107] op_sel_hi:[1,0]
	v_pk_mul_f32 v[118:119], v[130:131], v[106:107] op_sel_hi:[1,0]
	v_pk_mul_f32 v[120:121], v[132:133], v[106:107] op_sel_hi:[1,0]
	v_pk_mul_f32 v[122:123], v[136:137], v[106:107] op_sel_hi:[1,0]
	v_pk_mul_f32 v[106:107], v[114:115], v[106:107] op_sel_hi:[1,0]
	v_pk_mul_f32 v[110:111], v[20:21], v[110:111]
	v_pk_mul_f32 v[108:109], v[22:23], v[108:109]
	v_pk_mul_f32 v[114:115], v[16:17], v[116:117]
	v_pk_mul_f32 v[112:113], v[18:19], v[112:113]
	v_pk_mul_f32 v[116:117], v[52:53], v[120:121]
	v_pk_mul_f32 v[118:119], v[54:55], v[118:119]
	v_pk_mul_f32 v[106:107], v[48:49], v[106:107]
	v_pk_mul_f32 v[120:121], v[50:51], v[122:123]
	v_pk_fma_f32 v[108:109], v[82:83], v[108:109], v[30:31]
	v_pk_fma_f32 v[110:111], v[84:85], v[110:111], v[28:29]
	v_pk_fma_f32 v[112:113], v[86:87], v[112:113], v[26:27]
	v_pk_fma_f32 v[114:115], v[88:89], v[114:115], v[24:25]
	v_pk_fma_f32 v[118:119], v[90:91], v[118:119], v[62:63]
	v_pk_fma_f32 v[116:117], v[92:93], v[116:117], v[60:61]
	v_pk_fma_f32 v[120:121], v[94:95], v[120:121], v[58:59]
	v_pk_fma_f32 v[122:123], v[96:97], v[106:107], v[56:57]
	v_cvt_pk_bf16_f32 v106, v110, v111
	v_cvt_pk_bf16_f32 v107, v108, v109
	v_cvt_pk_bf16_f32 v108, v114, v115
	v_cvt_pk_bf16_f32 v109, v112, v113
	v_cvt_pk_bf16_f32 v110, v116, v117
	v_cvt_pk_bf16_f32 v111, v118, v119
	v_cvt_pk_bf16_f32 v112, v122, v123
	v_cvt_pk_bf16_f32 v113, v120, v121
	global_store_dwordx4 v[124:125], v[106:109], off sc1
	global_store_dwordx4 v[124:125], v[110:113], off offset:1024 sc1
	s_cselect_b32 s62, 1, 0
	s_cmp_eq_u32 s5, 2
	s_cbranch_scc0 .Lrpfr20B_b
	s_waitcnt vmcnt(12)
	v_mov_b32_e32 v106, v240
	v_mov_b32_e32 v107, v241
	v_mov_b32_e32 v108, v242
	v_mov_b32_e32 v109, v243
	v_mov_b32_e32 v110, v244
	v_mov_b32_e32 v111, v245
	v_mov_b32_e32 v112, v246
	v_mov_b32_e32 v113, v247
	v_mov_b32_e32 v114, v248
	v_mov_b32_e32 v115, v249
	v_mov_b32_e32 v116, v250
	v_mov_b32_e32 v117, v251
	v_mov_b32_e32 v118, v252
	v_mov_b32_e32 v119, v253
	v_mov_b32_e32 v120, v254
	v_mov_b32_e32 v121, v255
	s_branch .Lrpfr20B_d

.Lrpfr20B_d:
	s_cmp_lg_u32 s62, 0
	s_nop 0
	s_nop 0
	v_lshlrev_b32_e32 v122, 16, v106
	v_and_b32_e32 v123, 0xffff0000, v106
	s_nop 0
	v_and_b32_e32 v133, 0xffff0000, v116
	v_and_b32_e32 v132, 0xffff0000, v114
	v_lshlrev_b32_e32 v131, 16, v116
	v_lshlrev_b32_e32 v130, 16, v114
	v_lshlrev_b32_e32 v134, 16, v115
	v_and_b32_e32 v116, 0xffff0000, v115
	s_nop 0
	v_lshlrev_b32_e32 v115, 16, v118
	v_lshlrev_b32_e32 v114, 16, v120
	v_and_b32_e32 v137, 0xffff0000, v118
	v_and_b32_e32 v136, 0xffff0000, v120
	v_lshlrev_b32_e32 v138, 16, v121
	v_and_b32_e32 v118, 0xffff0000, v121
	v_pk_mul_f32 v[120:121], v[132:133], v[132:133]
	v_lshlrev_b32_e32 v135, 16, v117
	v_pk_mul_f32 v[140:141], v[136:137], v[136:137]
	v_pk_fma_f32 v[120:121], v[130:131], v[130:131], v[120:121]
	v_and_b32_e32 v117, 0xffff0000, v117
	v_lshlrev_b32_e32 v139, 16, v119
	v_mov_b32_e32 v150, v130
	v_mov_b32_e32 v151, v132
	v_mov_b32_e32 v132, v131
	v_pk_fma_f32 v[130:131], v[114:115], v[114:115], v[140:141]
	v_pk_fma_f32 v[120:121], v[134:135], v[134:135], v[120:121]
	v_and_b32_e32 v119, 0xffff0000, v119
	v_pk_fma_f32 v[130:131], v[138:139], v[138:139], v[130:131]
	v_pk_fma_f32 v[120:121], v[116:117], v[116:117], v[120:121]
	v_mov_b32_e32 v152, v139
	v_mov_b32_e32 v153, v119
	v_mov_b32_e32 v139, v118
	v_pk_fma_f32 v[118:119], v[118:119], v[118:119], v[130:131]
	v_add_f32_e32 v120, v120, v121
	v_add_f32_e32 v119, v120, v119
	v_add_f32_e32 v118, v118, v119
	v_mov_b32_e32 v119, v118
	v_mov_b32_e32 v160, v118
	s_nop 1
	v_permlane32_swap_b32_e32 v119, v160
	v_mov_b32_e32 v142, v134
	v_mov_b32_e32 v143, v116
	v_mov_b32_e32 v116, v135
	v_mov_b32_e32 v154, v115
	s_waitcnt lgkmcnt(0)
	v_add_f32_e32 v118, v119, v160
	v_mov_b32_e32 v119, v118
	v_mov_b32_e32 v160, v118
	s_nop 1
	v_permlane16_swap_b32_e32 v119, v160
	v_mov_b32_e32 v155, v137
	v_mov_b32_e32 v115, v136
	v_lshlrev_b32_e32 v106, 16, v107
	v_and_b32_e32 v107, 0xffff0000, v107
	s_waitcnt lgkmcnt(0)
	v_add_f32_e32 v118, v119, v160
	s_nop 1
	v_mov_b32_dpp v119, v118 row_ror:8 row_mask:0xf bank_mask:0xf
	v_lshlrev_b32_e32 v124, 16, v108
	v_and_b32_e32 v125, 0xffff0000, v108
	v_lshlrev_b32_e32 v108, 16, v109
	v_and_b32_e32 v109, 0xffff0000, v109
	s_waitcnt lgkmcnt(0)
	v_add_f32_e32 v118, v118, v119
	s_nop 1
	v_mov_b32_dpp v119, v118 row_ror:4 row_mask:0xf bank_mask:0xf
	v_lshlrev_b32_e32 v126, 16, v110
	v_and_b32_e32 v127, 0xffff0000, v110
	v_lshlrev_b32_e32 v110, 16, v111
	v_and_b32_e32 v111, 0xffff0000, v111
	s_waitcnt lgkmcnt(0)
	v_add_f32_e32 v118, v118, v119
	s_nop 1
	v_mov_b32_dpp v119, v118 row_ror:2 row_mask:0xf bank_mask:0xf
	v_lshlrev_b32_e32 v128, 16, v112
	v_and_b32_e32 v129, 0xffff0000, v112
	v_lshlrev_b32_e32 v112, 16, v113
	v_and_b32_e32 v113, 0xffff0000, v113
	s_waitcnt lgkmcnt(0)
	v_add_f32_e32 v118, v118, v119
	s_nop 1
	v_mov_b32_dpp v119, v118 row_ror:1 row_mask:0xf bank_mask:0xf
	s_waitcnt lgkmcnt(0)
	v_add_f32_e32 v118, v118, v119
	v_fmamk_f32 v118, v118, 0x3a800000, v104
	v_mul_f32_e32 v119, 0x4b800000, v118
	v_cmp_gt_f32_e32 vcc, s3, v118
	s_nop 1
	v_cndmask_b32_e32 v118, v118, v119, vcc
	v_rsq_f32_e32 v118, v118
	s_nop 0
	v_mul_f32_e32 v119, 0x45800000, v118
	v_cndmask_b32_e32 v118, v118, v119, vcc
	v_pk_mul_f32 v[120:121], v[118:119], v[142:143] op_sel_hi:[0,1]
	v_pk_mul_f32 v[130:131], v[118:119], v[150:151] op_sel_hi:[0,1]
	v_pk_mul_f32 v[116:117], v[118:119], v[116:117] op_sel_hi:[0,1]
	v_pk_mul_f32 v[132:133], v[118:119], v[132:133] op_sel_hi:[0,1]
	v_pk_mul_f32 v[134:135], v[118:119], v[152:153] op_sel_hi:[0,1]
	v_pk_mul_f32 v[136:137], v[118:119], v[154:155] op_sel_hi:[0,1]
	v_pk_mul_f32 v[138:139], v[118:119], v[138:139] op_sel_hi:[0,1]
	v_pk_mul_f32 v[114:115], v[118:119], v[114:115] op_sel_hi:[0,1]
	v_pk_mul_f32 v[118:119], v[4:5], v[130:131]
	v_pk_mul_f32 v[120:121], v[6:7], v[120:121]
	v_pk_mul_f32 v[130:131], v[0:1], v[132:133]
	v_pk_mul_f32 v[116:117], v[2:3], v[116:117]
	v_pk_mul_f32 v[132:133], v[36:37], v[136:137]
	v_pk_mul_f32 v[134:135], v[38:39], v[134:135]
	v_pk_mul_f32 v[114:115], v[32:33], v[114:115]
	v_pk_mul_f32 v[136:137], v[34:35], v[138:139]
	v_pk_fma_f32 v[120:121], v[14:15], v[120:121], v[106:107]
	v_pk_fma_f32 v[118:119], v[12:13], v[118:119], v[122:123]
	v_pk_fma_f32 v[116:117], v[10:11], v[116:117], v[108:109]
	v_pk_fma_f32 v[122:123], v[8:9], v[130:131], v[124:125]
	v_pk_fma_f32 v[124:125], v[46:47], v[134:135], v[110:111]
	v_pk_fma_f32 v[126:127], v[44:45], v[132:133], v[126:127]
	v_pk_fma_f32 v[130:131], v[42:43], v[136:137], v[112:113]
	v_pk_fma_f32 v[114:115], v[40:41], v[114:115], v[128:129]
	v_cvt_pk_bf16_f32 v106, v118, v119
	v_cvt_pk_bf16_f32 v107, v120, v121
	v_cvt_pk_bf16_f32 v108, v122, v123
	v_cvt_pk_bf16_f32 v109, v116, v117
	v_mov_b32_e32 v132, v119
	v_mov_b32_e32 v133, v123
	v_cvt_pk_bf16_f32 v110, v126, v127
	v_cvt_pk_bf16_f32 v111, v124, v125
	v_cvt_pk_bf16_f32 v112, v114, v115
	v_cvt_pk_bf16_f32 v113, v130, v131
	v_mov_b32_e32 v128, v118
	v_mov_b32_e32 v129, v122
	v_mov_b32_e32 v140, v115
	v_mov_b32_e32 v141, v127
	global_store_dwordx4 v[100:101], v[106:109], off sc1
	global_store_dwordx4 v[100:101], v[110:113], off offset:1024 sc1
	v_pk_mul_f32 v[100:101], v[132:133], v[132:133]
	v_mov_b32_e32 v134, v120
	v_mov_b32_e32 v135, v116
	v_mov_b32_e32 v138, v114
	v_mov_b32_e32 v139, v126
	v_pk_mul_f32 v[106:107], v[140:141], v[140:141]
	v_pk_fma_f32 v[100:101], v[128:129], v[128:129], v[100:101]
	v_mov_b32_e32 v136, v121
	v_mov_b32_e32 v137, v117
	v_mov_b32_e32 v142, v130
	v_mov_b32_e32 v143, v124
	v_pk_fma_f32 v[106:107], v[138:139], v[138:139], v[106:107]
	v_pk_fma_f32 v[100:101], v[134:135], v[134:135], v[100:101]
	v_mov_b32_e32 v150, v131
	v_mov_b32_e32 v151, v125
	v_pk_fma_f32 v[106:107], v[142:143], v[142:143], v[106:107]
	v_pk_fma_f32 v[100:101], v[136:137], v[136:137], v[100:101]
	v_pk_fma_f32 v[106:107], v[150:151], v[150:151], v[106:107]
	v_add_f32_e32 v100, v100, v101
	v_add_f32_e32 v100, v107, v100
	v_add_f32_e32 v100, v106, v100
	v_mov_b32_e32 v101, v100
	v_mov_b32_e32 v160, v100
	s_nop 1
	v_permlane32_swap_b32_e32 v101, v160
	s_waitcnt lgkmcnt(0)
	v_add_f32_e32 v100, v101, v160
	v_mov_b32_e32 v101, v100
	v_mov_b32_e32 v160, v100
	s_nop 1
	v_permlane16_swap_b32_e32 v101, v160
	s_waitcnt lgkmcnt(0)
	v_add_f32_e32 v100, v101, v160
	s_nop 1
	v_mov_b32_dpp v101, v100 row_ror:8 row_mask:0xf bank_mask:0xf
	s_waitcnt lgkmcnt(0)
	v_add_f32_e32 v100, v100, v101
	s_nop 1
	v_mov_b32_dpp v101, v100 row_ror:4 row_mask:0xf bank_mask:0xf
	s_waitcnt lgkmcnt(0)
	v_add_f32_e32 v100, v100, v101
	s_nop 1
	v_mov_b32_dpp v101, v100 row_ror:2 row_mask:0xf bank_mask:0xf
	s_waitcnt lgkmcnt(0)
	v_add_f32_e32 v100, v100, v101
	s_nop 1
	v_mov_b32_dpp v101, v100 row_ror:1 row_mask:0xf bank_mask:0xf
	s_waitcnt lgkmcnt(0)
	v_add_f32_e32 v100, v100, v101
	v_fmamk_f32 v100, v100, 0x3a800000, v104
	v_mul_f32_e32 v101, 0x4b800000, v100
	v_cmp_gt_f32_e32 vcc, s3, v100
	s_nop 1
	v_cndmask_b32_e32 v100, v100, v101, vcc
	v_rsq_f32_e32 v100, v100
	s_nop 0
	v_mul_f32_e32 v101, 0x45800000, v100
	v_cndmask_b32_e32 v100, v100, v101, vcc
	v_pk_mul_f32 v[106:107], v[120:121], v[100:101] op_sel_hi:[1,0]
	v_pk_mul_f32 v[108:109], v[118:119], v[100:101] op_sel_hi:[1,0]
	v_pk_mul_f32 v[110:111], v[116:117], v[100:101] op_sel_hi:[1,0]
	v_pk_mul_f32 v[112:113], v[122:123], v[100:101] op_sel_hi:[1,0]
	v_pk_mul_f32 v[116:117], v[124:125], v[100:101] op_sel_hi:[1,0]
	v_pk_mul_f32 v[118:119], v[126:127], v[100:101] op_sel_hi:[1,0]
	v_pk_mul_f32 v[120:121], v[130:131], v[100:101] op_sel_hi:[1,0]
	v_pk_mul_f32 v[100:101], v[114:115], v[100:101] op_sel_hi:[1,0]
	v_pk_mul_f32 v[108:109], v[20:21], v[108:109]
	v_pk_mul_f32 v[106:107], v[22:23], v[106:107]
	v_pk_mul_f32 v[112:113], v[16:17], v[112:113]
	v_pk_mul_f32 v[110:111], v[18:19], v[110:111]
	v_pk_mul_f32 v[114:115], v[52:53], v[118:119]
	v_pk_mul_f32 v[116:117], v[54:55], v[116:117]
	v_pk_mul_f32 v[100:101], v[48:49], v[100:101]
	v_pk_mul_f32 v[118:119], v[50:51], v[120:121]
	v_pk_fma_f32 v[120:121], v[82:83], v[106:107], v[30:31]
	v_pk_fma_f32 v[106:107], v[84:85], v[108:109], v[28:29]
	v_pk_fma_f32 v[110:111], v[86:87], v[110:111], v[26:27]
	v_pk_fma_f32 v[108:109], v[88:89], v[112:113], v[24:25]
	v_pk_fma_f32 v[112:113], v[90:91], v[116:117], v[62:63]
	v_pk_fma_f32 v[114:115], v[92:93], v[114:115], v[60:61]
	v_pk_fma_f32 v[116:117], v[94:95], v[118:119], v[58:59]
	v_pk_fma_f32 v[100:101], v[96:97], v[100:101], v[56:57]
	v_cvt_pk_bf16_f32 v106, v106, v107
	v_cvt_pk_bf16_f32 v107, v120, v121
	v_cvt_pk_bf16_f32 v108, v108, v109
	v_cvt_pk_bf16_f32 v109, v110, v111
	v_cvt_pk_bf16_f32 v110, v114, v115
	v_cvt_pk_bf16_f32 v111, v112, v113
	v_cvt_pk_bf16_f32 v112, v100, v101
	v_cvt_pk_bf16_f32 v113, v116, v117
	global_store_dwordx4 v[98:99], v[106:109], off sc1
	global_store_dwordx4 v[98:99], v[110:113], off offset:1024 sc1
	s_cbranch_scc0 .LBB0_864
	v_add_u32_e32 v105, s0, v105
	v_cmp_lt_i32_e32 vcc, s4, v105
	s_or_b64 s[8:9], vcc, s[8:9]
	v_add_u32_e32 v102, s1, v102
	s_andn2_b64 exec, exec, s[8:9]
	s_cbranch_execnz .LBB0_863

.Lrpfr11A_d:
	s_nop 0
	v_ashrrev_i32_e32 v101, 31, v100
	v_lshl_add_u64 v[124:125], v[70:71], 0, v[98:99]
	v_lshlrev_b64 v[98:99], 11, v[100:101]
	v_lshl_add_u64 v[100:101], v[68:69], 0, v[98:99]
	v_lshl_add_u64 v[126:127], v[66:67], 0, v[98:99]
	s_add_i32 s5, s5, 2
	s_cmp_eq_u32 s5, 4
	v_lshl_add_u64 v[98:99], v[70:71], 0, v[98:99]
	s_nop 0
	v_lshlrev_b32_e32 v128, 16, v106
	v_and_b32_e32 v129, 0xffff0000, v106
	s_nop 0
	v_and_b32_e32 v139, 0xffff0000, v116
	v_and_b32_e32 v138, 0xffff0000, v114
	v_lshlrev_b32_e32 v137, 16, v116
	v_lshlrev_b32_e32 v136, 16, v114
	v_lshlrev_b32_e32 v140, 16, v115
	v_and_b32_e32 v116, 0xffff0000, v115
	s_nop 0
	v_lshlrev_b32_e32 v115, 16, v118
	v_lshlrev_b32_e32 v114, 16, v120
	v_and_b32_e32 v143, 0xffff0000, v118
	v_and_b32_e32 v142, 0xffff0000, v120
	v_lshlrev_b32_e32 v148, 16, v121
	v_and_b32_e32 v118, 0xffff0000, v121
	v_pk_mul_f32 v[120:121], v[138:139], v[138:139]
	v_lshlrev_b32_e32 v141, 16, v117
	v_pk_mul_f32 v[150:151], v[142:143], v[142:143]
	v_pk_fma_f32 v[120:121], v[136:137], v[136:137], v[120:121]
	v_and_b32_e32 v117, 0xffff0000, v117
	v_lshlrev_b32_e32 v149, 16, v119
	v_mov_b32_e32 v154, v136
	v_mov_b32_e32 v155, v138
	v_mov_b32_e32 v138, v137
	v_pk_fma_f32 v[136:137], v[114:115], v[114:115], v[150:151]
	v_pk_fma_f32 v[120:121], v[140:141], v[140:141], v[120:121]
	v_and_b32_e32 v119, 0xffff0000, v119
	v_pk_fma_f32 v[136:137], v[148:149], v[148:149], v[136:137]
	v_pk_fma_f32 v[120:121], v[116:117], v[116:117], v[120:121]
	v_mov_b32_e32 v156, v149
	v_mov_b32_e32 v157, v119
	v_mov_b32_e32 v149, v118
	v_pk_fma_f32 v[118:119], v[118:119], v[118:119], v[136:137]
	v_add_f32_e32 v120, v120, v121
	v_add_f32_e32 v119, v120, v119
	v_add_f32_e32 v118, v118, v119
	v_mov_b32_e32 v119, v118
	v_mov_b32_e32 v160, v118
	s_nop 1
	v_permlane32_swap_b32_e32 v119, v160
	v_mov_b32_e32 v152, v140
	v_mov_b32_e32 v153, v116
	v_mov_b32_e32 v116, v141
	v_mov_b32_e32 v158, v115
	s_waitcnt lgkmcnt(0)
	v_add_f32_e32 v118, v119, v160
	v_mov_b32_e32 v119, v118
	v_mov_b32_e32 v160, v118
	s_nop 1
	v_permlane16_swap_b32_e32 v119, v160
	v_mov_b32_e32 v159, v143
	v_mov_b32_e32 v115, v142
	v_lshlrev_b32_e32 v106, 16, v107
	v_and_b32_e32 v107, 0xffff0000, v107
	s_waitcnt lgkmcnt(0)
	v_add_f32_e32 v118, v119, v160
	s_nop 1
	v_mov_b32_dpp v119, v118 row_ror:8 row_mask:0xf bank_mask:0xf
	v_lshlrev_b32_e32 v130, 16, v108
	v_and_b32_e32 v131, 0xffff0000, v108
	v_lshlrev_b32_e32 v108, 16, v109
	v_and_b32_e32 v109, 0xffff0000, v109
	s_waitcnt lgkmcnt(0)
	v_add_f32_e32 v118, v118, v119
	s_nop 1
	v_mov_b32_dpp v119, v118 row_ror:4 row_mask:0xf bank_mask:0xf
	v_lshlrev_b32_e32 v132, 16, v110
	v_and_b32_e32 v133, 0xffff0000, v110
	v_lshlrev_b32_e32 v110, 16, v111
	v_and_b32_e32 v111, 0xffff0000, v111
	s_waitcnt lgkmcnt(0)
	v_add_f32_e32 v118, v118, v119
	s_nop 1
	v_mov_b32_dpp v119, v118 row_ror:2 row_mask:0xf bank_mask:0xf
	v_lshlrev_b32_e32 v134, 16, v112
	v_and_b32_e32 v135, 0xffff0000, v112
	v_lshlrev_b32_e32 v112, 16, v113
	v_and_b32_e32 v113, 0xffff0000, v113
	s_waitcnt lgkmcnt(0)
	v_add_f32_e32 v118, v118, v119
	s_nop 1
	v_mov_b32_dpp v119, v118 row_ror:1 row_mask:0xf bank_mask:0xf
	s_waitcnt lgkmcnt(0)
	v_add_f32_e32 v118, v118, v119
	v_fmamk_f32 v118, v118, 0x3a800000, v104
	v_mul_f32_e32 v119, 0x4b800000, v118
	v_cmp_gt_f32_e32 vcc, s3, v118
	s_nop 1
	v_cndmask_b32_e32 v118, v118, v119, vcc
	v_rsq_f32_e32 v118, v118
	s_nop 0
	v_mul_f32_e32 v119, 0x45800000, v118
	v_cndmask_b32_e32 v118, v118, v119, vcc
	v_pk_mul_f32 v[120:121], v[118:119], v[152:153] op_sel_hi:[0,1]
	v_pk_mul_f32 v[136:137], v[118:119], v[154:155] op_sel_hi:[0,1]
	v_pk_mul_f32 v[116:117], v[118:119], v[116:117] op_sel_hi:[0,1]
	v_pk_mul_f32 v[138:139], v[118:119], v[138:139] op_sel_hi:[0,1]
	v_pk_mul_f32 v[140:141], v[118:119], v[156:157] op_sel_hi:[0,1]
	v_pk_mul_f32 v[142:143], v[118:119], v[158:159] op_sel_hi:[0,1]
	v_pk_mul_f32 v[148:149], v[118:119], v[148:149] op_sel_hi:[0,1]
	v_pk_mul_f32 v[114:115], v[118:119], v[114:115] op_sel_hi:[0,1]
	v_pk_mul_f32 v[118:119], v[4:5], v[136:137]
	v_pk_mul_f32 v[120:121], v[6:7], v[120:121]
	v_pk_mul_f32 v[136:137], v[0:1], v[138:139]
	v_pk_mul_f32 v[116:117], v[2:3], v[116:117]
	v_pk_mul_f32 v[138:139], v[36:37], v[142:143]
	v_pk_mul_f32 v[140:141], v[38:39], v[140:141]
	v_pk_mul_f32 v[114:115], v[32:33], v[114:115]
	v_pk_mul_f32 v[142:143], v[34:35], v[148:149]
	v_pk_fma_f32 v[120:121], v[14:15], v[120:121], v[106:107]
	v_pk_fma_f32 v[118:119], v[12:13], v[118:119], v[128:129]
	v_pk_fma_f32 v[116:117], v[10:11], v[116:117], v[108:109]
	v_pk_fma_f32 v[128:129], v[8:9], v[136:137], v[130:131]
	v_pk_fma_f32 v[130:131], v[46:47], v[140:141], v[110:111]
	v_pk_fma_f32 v[132:133], v[44:45], v[138:139], v[132:133]
	v_pk_fma_f32 v[136:137], v[42:43], v[142:143], v[112:113]
	v_pk_fma_f32 v[114:115], v[40:41], v[114:115], v[134:135]
	v_cvt_pk_bf16_f32 v106, v118, v119
	v_cvt_pk_bf16_f32 v107, v120, v121
	v_cvt_pk_bf16_f32 v108, v128, v129
	v_cvt_pk_bf16_f32 v109, v116, v117
	v_mov_b32_e32 v138, v119
	v_mov_b32_e32 v139, v129
	v_cvt_pk_bf16_f32 v110, v132, v133
	v_cvt_pk_bf16_f32 v111, v130, v131
	v_cvt_pk_bf16_f32 v112, v114, v115
	v_cvt_pk_bf16_f32 v113, v136, v137
	v_mov_b32_e32 v134, v118
	v_mov_b32_e32 v135, v128
	v_mov_b32_e32 v150, v115
	v_mov_b32_e32 v151, v133
	global_store_dwordx4 v[122:123], v[106:109], off sc1
	global_store_dwordx4 v[122:123], v[110:113], off offset:1024 sc1
	v_mov_b32_e32 v140, v120
	v_pk_mul_f32 v[106:107], v[138:139], v[138:139]
	v_mov_b32_e32 v141, v116
	v_mov_b32_e32 v148, v114
	v_mov_b32_e32 v149, v132
	v_pk_mul_f32 v[108:109], v[150:151], v[150:151]
	v_pk_fma_f32 v[106:107], v[134:135], v[134:135], v[106:107]
	v_mov_b32_e32 v142, v121
	v_mov_b32_e32 v143, v117
	v_mov_b32_e32 v152, v136
	v_mov_b32_e32 v153, v130
	v_pk_fma_f32 v[108:109], v[148:149], v[148:149], v[108:109]
	v_pk_fma_f32 v[106:107], v[140:141], v[140:141], v[106:107]
	v_mov_b32_e32 v154, v137
	v_mov_b32_e32 v155, v131
	v_pk_fma_f32 v[108:109], v[152:153], v[152:153], v[108:109]
	v_pk_fma_f32 v[106:107], v[142:143], v[142:143], v[106:107]
	v_pk_fma_f32 v[108:109], v[154:155], v[154:155], v[108:109]
	v_add_f32_e32 v106, v106, v107
	v_add_f32_e32 v106, v109, v106
	v_add_f32_e32 v106, v108, v106
	v_mov_b32_e32 v107, v106
	v_mov_b32_e32 v160, v106
	s_nop 1
	v_permlane32_swap_b32_e32 v107, v160
	s_waitcnt lgkmcnt(0)
	v_add_f32_e32 v106, v107, v160
	v_mov_b32_e32 v107, v106
	v_mov_b32_e32 v160, v106
	s_nop 1
	v_permlane16_swap_b32_e32 v107, v160
	s_waitcnt lgkmcnt(0)
	v_add_f32_e32 v106, v107, v160
	s_nop 1
	v_mov_b32_dpp v107, v106 row_ror:8 row_mask:0xf bank_mask:0xf
	s_waitcnt lgkmcnt(0)
	v_add_f32_e32 v106, v106, v107
	s_nop 1
	v_mov_b32_dpp v107, v106 row_ror:4 row_mask:0xf bank_mask:0xf
	s_waitcnt lgkmcnt(0)
	v_add_f32_e32 v106, v106, v107
	s_nop 1
	v_mov_b32_dpp v107, v106 row_ror:2 row_mask:0xf bank_mask:0xf
	s_waitcnt lgkmcnt(0)
	v_add_f32_e32 v106, v106, v107
	s_nop 1
	v_mov_b32_dpp v107, v106 row_ror:1 row_mask:0xf bank_mask:0xf
	s_waitcnt lgkmcnt(0)
	v_add_f32_e32 v106, v106, v107
	v_fmamk_f32 v106, v106, 0x3a800000, v104
	v_mul_f32_e32 v107, 0x4b800000, v106
	v_cmp_gt_f32_e32 vcc, s3, v106
	s_nop 1
	v_cndmask_b32_e32 v106, v106, v107, vcc
	v_rsq_f32_e32 v106, v106
	s_nop 0
	v_mul_f32_e32 v107, 0x45800000, v106
	v_cndmask_b32_e32 v106, v106, v107, vcc
	v_pk_mul_f32 v[108:109], v[120:121], v[106:107] op_sel_hi:[1,0]
	v_pk_mul_f32 v[110:111], v[118:119], v[106:107] op_sel_hi:[1,0]
	v_pk_mul_f32 v[112:113], v[116:117], v[106:107] op_sel_hi:[1,0]
	v_pk_mul_f32 v[116:117], v[128:129], v[106:107] op_sel_hi:[1,0]
	v_pk_mul_f32 v[118:119], v[130:131], v[106:107] op_sel_hi:[1,0]
	v_pk_mul_f32 v[120:121], v[132:133], v[106:107] op_sel_hi:[1,0]
	v_pk_mul_f32 v[122:123], v[136:137], v[106:107] op_sel_hi:[1,0]
	v_pk_mul_f32 v[106:107], v[114:115], v[106:107] op_sel_hi:[1,0]
	v_pk_mul_f32 v[110:111], v[20:21], v[110:111]
	v_pk_mul_f32 v[108:109], v[22:23], v[108:109]
	v_pk_mul_f32 v[114:115], v[16:17], v[116:117]
	v_pk_mul_f32 v[112:113], v[18:19], v[112:113]
	v_pk_mul_f32 v[116:117], v[52:53], v[120:121]
	v_pk_mul_f32 v[118:119], v[54:55], v[118:119]
	v_pk_mul_f32 v[106:107], v[48:49], v[106:107]
	v_pk_mul_f32 v[120:121], v[50:51], v[122:123]
	v_pk_fma_f32 v[108:109], v[82:83], v[108:109], v[30:31]
	v_pk_fma_f32 v[110:111], v[84:85], v[110:111], v[28:29]
	v_pk_fma_f32 v[112:113], v[86:87], v[112:113], v[26:27]
	v_pk_fma_f32 v[114:115], v[88:89], v[114:115], v[24:25]
	v_pk_fma_f32 v[118:119], v[90:91], v[118:119], v[62:63]
	v_pk_fma_f32 v[116:117], v[92:93], v[116:117], v[60:61]
	v_pk_fma_f32 v[120:121], v[94:95], v[120:121], v[58:59]
	v_pk_fma_f32 v[122:123], v[96:97], v[106:107], v[56:57]
	v_cvt_pk_bf16_f32 v106, v110, v111
	v_cvt_pk_bf16_f32 v107, v108, v109
	v_cvt_pk_bf16_f32 v108, v114, v115
	v_cvt_pk_bf16_f32 v109, v112, v113
	v_cvt_pk_bf16_f32 v110, v116, v117
	v_cvt_pk_bf16_f32 v111, v118, v119
	v_cvt_pk_bf16_f32 v112, v122, v123
	v_cvt_pk_bf16_f32 v113, v120, v121
	global_store_dwordx4 v[124:125], v[106:109], off sc1
	global_store_dwordx4 v[124:125], v[110:113], off offset:1024 sc1
	s_cselect_b32 s62, 1, 0
	s_cmp_eq_u32 s5, 2
	s_cbranch_scc0 .Lrpfr11B_b
	s_waitcnt vmcnt(12)
	v_mov_b32_e32 v106, v240
	v_mov_b32_e32 v107, v241
	v_mov_b32_e32 v108, v242
	v_mov_b32_e32 v109, v243
	v_mov_b32_e32 v110, v244
	v_mov_b32_e32 v111, v245
	v_mov_b32_e32 v112, v246
	v_mov_b32_e32 v113, v247
	v_mov_b32_e32 v114, v248
	v_mov_b32_e32 v115, v249
	v_mov_b32_e32 v116, v250
	v_mov_b32_e32 v117, v251
	v_mov_b32_e32 v118, v252
	v_mov_b32_e32 v119, v253
	v_mov_b32_e32 v120, v254
	v_mov_b32_e32 v121, v255
	s_branch .Lrpfr11B_d

.Lrpfr11B_d:
	s_cmp_lg_u32 s62, 0
	s_nop 0
	s_nop 0
	v_lshlrev_b32_e32 v122, 16, v106
	v_and_b32_e32 v123, 0xffff0000, v106
	s_nop 0
	v_and_b32_e32 v133, 0xffff0000, v116
	v_and_b32_e32 v132, 0xffff0000, v114
	v_lshlrev_b32_e32 v131, 16, v116
	v_lshlrev_b32_e32 v130, 16, v114
	v_lshlrev_b32_e32 v134, 16, v115
	v_and_b32_e32 v116, 0xffff0000, v115
	s_nop 0
	v_lshlrev_b32_e32 v115, 16, v118
	v_lshlrev_b32_e32 v114, 16, v120
	v_and_b32_e32 v137, 0xffff0000, v118
	v_and_b32_e32 v136, 0xffff0000, v120
	v_lshlrev_b32_e32 v138, 16, v121
	v_and_b32_e32 v118, 0xffff0000, v121
	v_pk_mul_f32 v[120:121], v[132:133], v[132:133]
	v_lshlrev_b32_e32 v135, 16, v117
	v_pk_mul_f32 v[140:141], v[136:137], v[136:137]
	v_pk_fma_f32 v[120:121], v[130:131], v[130:131], v[120:121]
	v_and_b32_e32 v117, 0xffff0000, v117
	v_lshlrev_b32_e32 v139, 16, v119
	v_mov_b32_e32 v148, v130
	v_mov_b32_e32 v149, v132
	v_mov_b32_e32 v132, v131
	v_pk_fma_f32 v[130:131], v[114:115], v[114:115], v[140:141]
	v_pk_fma_f32 v[120:121], v[134:135], v[134:135], v[120:121]
	v_and_b32_e32 v119, 0xffff0000, v119
	v_pk_fma_f32 v[130:131], v[138:139], v[138:139], v[130:131]
	v_pk_fma_f32 v[120:121], v[116:117], v[116:117], v[120:121]
	v_mov_b32_e32 v150, v139
	v_mov_b32_e32 v151, v119
	v_mov_b32_e32 v139, v118
	v_pk_fma_f32 v[118:119], v[118:119], v[118:119], v[130:131]
	v_add_f32_e32 v120, v120, v121
	v_add_f32_e32 v119, v120, v119
	v_add_f32_e32 v118, v118, v119
	v_mov_b32_e32 v119, v118
	v_mov_b32_e32 v160, v118
	s_nop 1
	v_permlane32_swap_b32_e32 v119, v160
	v_mov_b32_e32 v142, v134
	v_mov_b32_e32 v143, v116
	v_mov_b32_e32 v116, v135
	v_mov_b32_e32 v152, v115
	s_waitcnt lgkmcnt(0)
	v_add_f32_e32 v118, v119, v160
	v_mov_b32_e32 v119, v118
	v_mov_b32_e32 v160, v118
	s_nop 1
	v_permlane16_swap_b32_e32 v119, v160
	v_mov_b32_e32 v153, v137
	v_mov_b32_e32 v115, v136
	v_lshlrev_b32_e32 v106, 16, v107
	v_and_b32_e32 v107, 0xffff0000, v107
	s_waitcnt lgkmcnt(0)
	v_add_f32_e32 v118, v119, v160
	s_nop 1
	v_mov_b32_dpp v119, v118 row_ror:8 row_mask:0xf bank_mask:0xf
	v_lshlrev_b32_e32 v124, 16, v108
	v_and_b32_e32 v125, 0xffff0000, v108
	v_lshlrev_b32_e32 v108, 16, v109
	v_and_b32_e32 v109, 0xffff0000, v109
	s_waitcnt lgkmcnt(0)
	v_add_f32_e32 v118, v118, v119
	s_nop 1
	v_mov_b32_dpp v119, v118 row_ror:4 row_mask:0xf bank_mask:0xf
	v_lshlrev_b32_e32 v126, 16, v110
	v_and_b32_e32 v127, 0xffff0000, v110
	v_lshlrev_b32_e32 v110, 16, v111
	v_and_b32_e32 v111, 0xffff0000, v111
	s_waitcnt lgkmcnt(0)
	v_add_f32_e32 v118, v118, v119
	s_nop 1
	v_mov_b32_dpp v119, v118 row_ror:2 row_mask:0xf bank_mask:0xf
	v_lshlrev_b32_e32 v128, 16, v112
	v_and_b32_e32 v129, 0xffff0000, v112
	v_lshlrev_b32_e32 v112, 16, v113
	v_and_b32_e32 v113, 0xffff0000, v113
	s_waitcnt lgkmcnt(0)
	v_add_f32_e32 v118, v118, v119
	s_nop 1
	v_mov_b32_dpp v119, v118 row_ror:1 row_mask:0xf bank_mask:0xf
	s_waitcnt lgkmcnt(0)
	v_add_f32_e32 v118, v118, v119
	v_fmamk_f32 v118, v118, 0x3a800000, v104
	v_mul_f32_e32 v119, 0x4b800000, v118
	v_cmp_gt_f32_e32 vcc, s3, v118
	s_nop 1
	v_cndmask_b32_e32 v118, v118, v119, vcc
	v_rsq_f32_e32 v118, v118
	s_nop 0
	v_mul_f32_e32 v119, 0x45800000, v118
	v_cndmask_b32_e32 v118, v118, v119, vcc
	v_pk_mul_f32 v[120:121], v[118:119], v[142:143] op_sel_hi:[0,1]
	v_pk_mul_f32 v[130:131], v[118:119], v[148:149] op_sel_hi:[0,1]
	v_pk_mul_f32 v[116:117], v[118:119], v[116:117] op_sel_hi:[0,1]
	v_pk_mul_f32 v[132:133], v[118:119], v[132:133] op_sel_hi:[0,1]
	v_pk_mul_f32 v[134:135], v[118:119], v[150:151] op_sel_hi:[0,1]
	v_pk_mul_f32 v[136:137], v[118:119], v[152:153] op_sel_hi:[0,1]
	v_pk_mul_f32 v[138:139], v[118:119], v[138:139] op_sel_hi:[0,1]
	v_pk_mul_f32 v[114:115], v[118:119], v[114:115] op_sel_hi:[0,1]
	v_pk_mul_f32 v[118:119], v[4:5], v[130:131]
	v_pk_mul_f32 v[120:121], v[6:7], v[120:121]
	v_pk_mul_f32 v[130:131], v[0:1], v[132:133]
	v_pk_mul_f32 v[116:117], v[2:3], v[116:117]
	v_pk_mul_f32 v[132:133], v[36:37], v[136:137]
	v_pk_mul_f32 v[134:135], v[38:39], v[134:135]
	v_pk_mul_f32 v[114:115], v[32:33], v[114:115]
	v_pk_mul_f32 v[136:137], v[34:35], v[138:139]
	v_pk_fma_f32 v[120:121], v[14:15], v[120:121], v[106:107]
	v_pk_fma_f32 v[118:119], v[12:13], v[118:119], v[122:123]
	v_pk_fma_f32 v[116:117], v[10:11], v[116:117], v[108:109]
	v_pk_fma_f32 v[122:123], v[8:9], v[130:131], v[124:125]
	v_pk_fma_f32 v[124:125], v[46:47], v[134:135], v[110:111]
	v_pk_fma_f32 v[126:127], v[44:45], v[132:133], v[126:127]
	v_pk_fma_f32 v[130:131], v[42:43], v[136:137], v[112:113]
	v_pk_fma_f32 v[114:115], v[40:41], v[114:115], v[128:129]
	v_cvt_pk_bf16_f32 v106, v118, v119
	v_cvt_pk_bf16_f32 v107, v120, v121
	v_cvt_pk_bf16_f32 v108, v122, v123
	v_cvt_pk_bf16_f32 v109, v116, v117
	v_mov_b32_e32 v132, v119
	v_mov_b32_e32 v133, v123
	v_cvt_pk_bf16_f32 v110, v126, v127
	v_cvt_pk_bf16_f32 v111, v124, v125
	v_cvt_pk_bf16_f32 v112, v114, v115
	v_cvt_pk_bf16_f32 v113, v130, v131
	v_mov_b32_e32 v128, v118
	v_mov_b32_e32 v129, v122
	v_mov_b32_e32 v140, v115
	v_mov_b32_e32 v141, v127
	global_store_dwordx4 v[100:101], v[106:109], off sc1
	global_store_dwordx4 v[100:101], v[110:113], off offset:1024 sc1
	v_pk_mul_f32 v[100:101], v[132:133], v[132:133]
	v_mov_b32_e32 v134, v120
	v_mov_b32_e32 v135, v116
	v_mov_b32_e32 v138, v114
	v_mov_b32_e32 v139, v126
	v_pk_mul_f32 v[106:107], v[140:141], v[140:141]
	v_pk_fma_f32 v[100:101], v[128:129], v[128:129], v[100:101]
	v_mov_b32_e32 v136, v121
	v_mov_b32_e32 v137, v117
	v_mov_b32_e32 v142, v130
	v_mov_b32_e32 v143, v124
	v_pk_fma_f32 v[106:107], v[138:139], v[138:139], v[106:107]
	v_pk_fma_f32 v[100:101], v[134:135], v[134:135], v[100:101]
	v_mov_b32_e32 v148, v131
	v_mov_b32_e32 v149, v125
	v_pk_fma_f32 v[106:107], v[142:143], v[142:143], v[106:107]
	v_pk_fma_f32 v[100:101], v[136:137], v[136:137], v[100:101]
	v_pk_fma_f32 v[106:107], v[148:149], v[148:149], v[106:107]
	v_add_f32_e32 v100, v100, v101
	v_add_f32_e32 v100, v107, v100
	v_add_f32_e32 v100, v106, v100
	v_mov_b32_e32 v101, v100
	v_mov_b32_e32 v160, v100
	s_nop 1
	v_permlane32_swap_b32_e32 v101, v160
	s_waitcnt lgkmcnt(0)
	v_add_f32_e32 v100, v101, v160
	v_mov_b32_e32 v101, v100
	v_mov_b32_e32 v160, v100
	s_nop 1
	v_permlane16_swap_b32_e32 v101, v160
	s_waitcnt lgkmcnt(0)
	v_add_f32_e32 v100, v101, v160
	s_nop 1
	v_mov_b32_dpp v101, v100 row_ror:8 row_mask:0xf bank_mask:0xf
	s_waitcnt lgkmcnt(0)
	v_add_f32_e32 v100, v100, v101
	s_nop 1
	v_mov_b32_dpp v101, v100 row_ror:4 row_mask:0xf bank_mask:0xf
	s_waitcnt lgkmcnt(0)
	v_add_f32_e32 v100, v100, v101
	s_nop 1
	v_mov_b32_dpp v101, v100 row_ror:2 row_mask:0xf bank_mask:0xf
	s_waitcnt lgkmcnt(0)
	v_add_f32_e32 v100, v100, v101
	s_nop 1
	v_mov_b32_dpp v101, v100 row_ror:1 row_mask:0xf bank_mask:0xf
	s_waitcnt lgkmcnt(0)
	v_add_f32_e32 v100, v100, v101
	v_fmamk_f32 v100, v100, 0x3a800000, v104
	v_mul_f32_e32 v101, 0x4b800000, v100
	v_cmp_gt_f32_e32 vcc, s3, v100
	s_nop 1
	v_cndmask_b32_e32 v100, v100, v101, vcc
	v_rsq_f32_e32 v100, v100
	s_nop 0
	v_mul_f32_e32 v101, 0x45800000, v100
	v_cndmask_b32_e32 v100, v100, v101, vcc
	v_pk_mul_f32 v[106:107], v[120:121], v[100:101] op_sel_hi:[1,0]
	v_pk_mul_f32 v[108:109], v[118:119], v[100:101] op_sel_hi:[1,0]
	v_pk_mul_f32 v[110:111], v[116:117], v[100:101] op_sel_hi:[1,0]
	v_pk_mul_f32 v[112:113], v[122:123], v[100:101] op_sel_hi:[1,0]
	v_pk_mul_f32 v[116:117], v[124:125], v[100:101] op_sel_hi:[1,0]
	v_pk_mul_f32 v[118:119], v[126:127], v[100:101] op_sel_hi:[1,0]
	v_pk_mul_f32 v[120:121], v[130:131], v[100:101] op_sel_hi:[1,0]
	v_pk_mul_f32 v[100:101], v[114:115], v[100:101] op_sel_hi:[1,0]
	v_pk_mul_f32 v[108:109], v[20:21], v[108:109]
	v_pk_mul_f32 v[106:107], v[22:23], v[106:107]
	v_pk_mul_f32 v[112:113], v[16:17], v[112:113]
	v_pk_mul_f32 v[110:111], v[18:19], v[110:111]
	v_pk_mul_f32 v[114:115], v[52:53], v[118:119]
	v_pk_mul_f32 v[116:117], v[54:55], v[116:117]
	v_pk_mul_f32 v[100:101], v[48:49], v[100:101]
	v_pk_mul_f32 v[118:119], v[50:51], v[120:121]
	v_pk_fma_f32 v[120:121], v[82:83], v[106:107], v[30:31]
	v_pk_fma_f32 v[106:107], v[84:85], v[108:109], v[28:29]
	v_pk_fma_f32 v[110:111], v[86:87], v[110:111], v[26:27]
	v_pk_fma_f32 v[108:109], v[88:89], v[112:113], v[24:25]
	v_pk_fma_f32 v[112:113], v[90:91], v[116:117], v[62:63]
	v_pk_fma_f32 v[114:115], v[92:93], v[114:115], v[60:61]
	v_pk_fma_f32 v[116:117], v[94:95], v[118:119], v[58:59]
	v_pk_fma_f32 v[100:101], v[96:97], v[100:101], v[56:57]
	v_cvt_pk_bf16_f32 v106, v106, v107
	v_cvt_pk_bf16_f32 v107, v120, v121
	v_cvt_pk_bf16_f32 v108, v108, v109
	v_cvt_pk_bf16_f32 v109, v110, v111
	v_cvt_pk_bf16_f32 v110, v114, v115
	v_cvt_pk_bf16_f32 v111, v112, v113
	v_cvt_pk_bf16_f32 v112, v100, v101
	v_cvt_pk_bf16_f32 v113, v116, v117
	global_store_dwordx4 v[98:99], v[106:109], off sc1
	global_store_dwordx4 v[98:99], v[110:113], off offset:1024 sc1
	s_cbranch_scc0 .LBB0_1291
	v_add_u32_e32 v105, s0, v105
	v_cmp_lt_i32_e32 vcc, s4, v105
	s_or_b64 s[8:9], vcc, s[8:9]
	v_add_u32_e32 v102, s1, v102
	s_andn2_b64 exec, exec, s[8:9]
	s_cbranch_execnz .LBB0_1290

.LBB0_1580:
	v_add_u32_e32 v46, s9, v48
	v_ashrrev_i32_e32 v47, 31, v46
	v_add_u32_e32 v52, 1, v46
	v_lshlrev_b64 v[54:55], 11, v[46:47]
	v_ashrrev_i32_e32 v53, 31, v52
	v_lshl_add_u64 v[68:69], v[34:35], 0, v[54:55]
	v_lshl_add_u64 v[70:71], v[36:37], 0, v[54:55]
	v_lshlrev_b64 v[72:73], 11, v[52:53]
	v_lshlrev_b64 v[74:75], 12, v[52:53]
	global_load_dwordx4 v[52:55], v[68:69], off
	global_load_dwordx4 v[56:59], v[68:69], off offset:1024
	global_load_dwordx4 v[60:63], v[70:71], off
	global_load_dwordx4 v[64:67], v[70:71], off offset:1024
	v_lshlrev_b64 v[46:47], 12, v[46:47]
	v_lshl_add_u64 v[68:69], v[34:35], 0, v[72:73]
	v_lshl_add_u64 v[70:71], v[36:37], 0, v[72:73]
	v_lshl_add_u64 v[72:73], v[42:43], 0, v[74:75]
	v_lshl_add_u64 v[46:47], v[42:43], 0, v[46:47]
	s_add_i32 s9, s9, 2
	s_cmp_eq_u32 s9, 4
	s_waitcnt vmcnt(3)
	v_lshlrev_b32_e32 v76, 16, v54
	s_waitcnt vmcnt(2)
	v_lshlrev_b32_e32 v80, 16, v56
	v_and_b32_e32 v81, 0xffff0000, v56
	v_lshlrev_b32_e32 v82, 16, v57
	v_and_b32_e32 v83, 0xffff0000, v57
	s_waitcnt vmcnt(1)
	v_and_b32_e32 v57, 0xffff0000, v62
	v_and_b32_e32 v56, 0xffff0000, v60
	v_and_b32_e32 v77, 0xffff0000, v54
	v_lshlrev_b32_e32 v78, 16, v55
	v_and_b32_e32 v79, 0xffff0000, v55
	v_lshlrev_b32_e32 v84, 16, v58
	v_and_b32_e32 v85, 0xffff0000, v58
	v_lshlrev_b32_e32 v55, 16, v62
	v_lshlrev_b32_e32 v54, 16, v60
	v_lshlrev_b32_e32 v58, 16, v61
	v_and_b32_e32 v62, 0xffff0000, v61
	s_waitcnt vmcnt(0)
	v_lshlrev_b32_e32 v61, 16, v64
	v_lshlrev_b32_e32 v60, 16, v66
	v_and_b32_e32 v89, 0xffff0000, v64
	v_and_b32_e32 v88, 0xffff0000, v66
	v_lshlrev_b32_e32 v90, 16, v67
	v_and_b32_e32 v64, 0xffff0000, v67
	v_pk_mul_f32 v[66:67], v[56:57], v[56:57]
	v_lshlrev_b32_e32 v86, 16, v59
	v_and_b32_e32 v87, 0xffff0000, v59
	v_lshlrev_b32_e32 v59, 16, v63
	v_pk_mul_f32 v[92:93], v[88:89], v[88:89]
	v_mov_b32_e32 v96, v54
	v_mov_b32_e32 v97, v56
	v_mov_b32_e32 v56, v55
	v_pk_fma_f32 v[54:55], v[54:55], v[54:55], v[66:67]
	v_and_b32_e32 v63, 0xffff0000, v63
	v_lshlrev_b32_e32 v91, 16, v65
	v_pk_fma_f32 v[66:67], v[60:61], v[60:61], v[92:93]
	v_pk_fma_f32 v[54:55], v[58:59], v[58:59], v[54:55]
	v_and_b32_e32 v65, 0xffff0000, v65
	v_pk_fma_f32 v[66:67], v[90:91], v[90:91], v[66:67]
	v_pk_fma_f32 v[54:55], v[62:63], v[62:63], v[54:55]
	v_mov_b32_e32 v98, v91
	v_mov_b32_e32 v99, v65
	v_mov_b32_e32 v91, v64
	v_pk_fma_f32 v[64:65], v[64:65], v[64:65], v[66:67]
	v_add_f32_e32 v51, v54, v55
	v_add_f32_e32 v51, v51, v65
	v_add_f32_e32 v51, v64, v51
	v_mov_b32_e32 v54, v51
	v_mov_b32_e32 v160, v51
	s_nop 1
	v_permlane32_swap_b32_e32 v54, v160
	v_mov_b32_e32 v94, v58
	v_mov_b32_e32 v95, v62
	v_mov_b32_e32 v100, v61
	v_mov_b32_e32 v101, v89
	s_waitcnt lgkmcnt(0)
	v_add_f32_e32 v51, v54, v160
	v_mov_b32_e32 v54, v51
	v_mov_b32_e32 v160, v51
	s_nop 1
	v_permlane16_swap_b32_e32 v54, v160
	v_mov_b32_e32 v61, v88
	v_mov_b32_e32 v62, v59
	v_lshlrev_b32_e32 v74, 16, v52
	v_and_b32_e32 v75, 0xffff0000, v52
	s_waitcnt lgkmcnt(0)
	v_add_f32_e32 v51, v54, v160
	s_nop 1
	v_mov_b32_dpp v54, v51 row_ror:8 row_mask:0xf bank_mask:0xf
	v_lshlrev_b32_e32 v52, 16, v53
	v_and_b32_e32 v53, 0xffff0000, v53
	s_waitcnt lgkmcnt(0)
	v_add_f32_e32 v51, v51, v54
	s_nop 1
	v_mov_b32_dpp v54, v51 row_ror:4 row_mask:0xf bank_mask:0xf
	s_waitcnt lgkmcnt(0)
	v_add_f32_e32 v51, v51, v54
	s_nop 1
	v_mov_b32_dpp v54, v51 row_ror:2 row_mask:0xf bank_mask:0xf
	s_waitcnt lgkmcnt(0)
	v_add_f32_e32 v51, v51, v54
	s_nop 1
	v_mov_b32_dpp v54, v51 row_ror:1 row_mask:0xf bank_mask:0xf
	s_waitcnt lgkmcnt(0)
	v_add_f32_e32 v51, v51, v54
	v_fmamk_f32 v51, v51, 0x3a800000, v50
	v_mul_f32_e32 v54, 0x4b800000, v51
	v_cmp_gt_f32_e32 vcc, s7, v51
	s_nop 1
	v_cndmask_b32_e32 v51, v51, v54, vcc
	v_rsq_f32_e32 v51, v51
	s_nop 0
	v_mul_f32_e32 v54, 0x45800000, v51
	v_cndmask_b32_e32 v54, v51, v54, vcc
	v_pk_mul_f32 v[58:59], v[54:55], v[94:95] op_sel_hi:[0,1]
	v_pk_mul_f32 v[64:65], v[54:55], v[96:97] op_sel_hi:[0,1]
	v_pk_mul_f32 v[62:63], v[54:55], v[62:63] op_sel_hi:[0,1]
	v_pk_mul_f32 v[56:57], v[54:55], v[56:57] op_sel_hi:[0,1]
	v_pk_mul_f32 v[66:67], v[54:55], v[98:99] op_sel_hi:[0,1]
	v_pk_mul_f32 v[88:89], v[54:55], v[100:101] op_sel_hi:[0,1]
	v_pk_mul_f32 v[90:91], v[54:55], v[90:91] op_sel_hi:[0,1]
	v_pk_mul_f32 v[54:55], v[54:55], v[60:61] op_sel_hi:[0,1]
	v_pk_mul_f32 v[60:61], v[4:5], v[64:65]
	v_pk_mul_f32 v[58:59], v[6:7], v[58:59]
	v_pk_mul_f32 v[56:57], v[0:1], v[56:57]
	v_pk_mul_f32 v[62:63], v[2:3], v[62:63]
	v_pk_mul_f32 v[64:65], v[20:21], v[88:89]
	v_pk_mul_f32 v[66:67], v[22:23], v[66:67]
	v_pk_mul_f32 v[88:89], v[16:17], v[54:55]
	v_pk_mul_f32 v[90:91], v[18:19], v[90:91]
	v_pk_fma_f32 v[54:55], v[14:15], v[58:59], v[52:53]
	v_pk_fma_f32 v[52:53], v[12:13], v[60:61], v[74:75]
	v_pk_fma_f32 v[58:59], v[10:11], v[62:63], v[78:79]
	v_pk_fma_f32 v[56:57], v[8:9], v[56:57], v[76:77]
	v_pk_fma_f32 v[62:63], v[30:31], v[66:67], v[82:83]
	v_pk_fma_f32 v[60:61], v[28:29], v[64:65], v[80:81]
	v_pk_fma_f32 v[66:67], v[26:27], v[90:91], v[86:87]
	v_pk_fma_f32 v[64:65], v[24:25], v[88:89], v[84:85]
	global_store_dwordx4 v[46:47], v[52:55], off nt
	global_store_dwordx4 v[46:47], v[56:59], off offset:16 nt
	global_store_dwordx4 v[46:47], v[60:63], off offset:2048 nt
	global_store_dwordx4 v[46:47], v[64:67], off offset:2064 nt
	global_load_dwordx4 v[52:55], v[68:69], off
	s_nop 0
	global_load_dwordx4 v[56:59], v[70:71], off
	global_load_dwordx4 v[60:63], v[70:71], off offset:1024
	global_load_dwordx4 v[64:67], v[68:69], off offset:1024
	s_waitcnt vmcnt(3)
	v_lshlrev_b32_e32 v68, 16, v54
	s_waitcnt vmcnt(2)
	v_and_b32_e32 v79, 0xffff0000, v58
	v_and_b32_e32 v78, 0xffff0000, v56
	v_and_b32_e32 v69, 0xffff0000, v54
	v_lshlrev_b32_e32 v70, 16, v55
	v_and_b32_e32 v71, 0xffff0000, v55
	v_lshlrev_b32_e32 v55, 16, v58
	v_lshlrev_b32_e32 v54, 16, v56
	v_lshlrev_b32_e32 v80, 16, v57
	v_and_b32_e32 v58, 0xffff0000, v57
	s_waitcnt vmcnt(1)
	v_lshlrev_b32_e32 v57, 16, v60
	v_lshlrev_b32_e32 v56, 16, v62
	v_and_b32_e32 v83, 0xffff0000, v60
	v_and_b32_e32 v82, 0xffff0000, v62
	v_lshlrev_b32_e32 v84, 16, v63
	v_and_b32_e32 v60, 0xffff0000, v63
	v_pk_mul_f32 v[62:63], v[78:79], v[78:79]
	v_lshlrev_b32_e32 v81, 16, v59
	v_pk_mul_f32 v[86:87], v[82:83], v[82:83]
	v_mov_b32_e32 v90, v54
	v_mov_b32_e32 v91, v78
	v_mov_b32_e32 v78, v55
	v_pk_fma_f32 v[54:55], v[54:55], v[54:55], v[62:63]
	v_and_b32_e32 v59, 0xffff0000, v59
	v_lshlrev_b32_e32 v85, 16, v61
	v_pk_fma_f32 v[62:63], v[56:57], v[56:57], v[86:87]
	v_pk_fma_f32 v[54:55], v[80:81], v[80:81], v[54:55]
	v_and_b32_e32 v61, 0xffff0000, v61
	v_pk_fma_f32 v[62:63], v[84:85], v[84:85], v[62:63]
	v_pk_fma_f32 v[54:55], v[58:59], v[58:59], v[54:55]
	v_mov_b32_e32 v92, v85
	v_mov_b32_e32 v93, v61
	v_mov_b32_e32 v85, v60
	v_pk_fma_f32 v[60:61], v[60:61], v[60:61], v[62:63]
	v_add_f32_e32 v51, v54, v55
	v_add_f32_e32 v51, v51, v61
	v_add_f32_e32 v51, v60, v51
	v_mov_b32_e32 v54, v51
	v_mov_b32_e32 v160, v51
	s_nop 1
	v_permlane32_swap_b32_e32 v54, v160
	v_mov_b32_e32 v88, v80
	v_mov_b32_e32 v89, v58
	v_mov_b32_e32 v94, v57
	v_mov_b32_e32 v95, v83
	s_waitcnt lgkmcnt(0)
	v_add_f32_e32 v51, v54, v160
	v_mov_b32_e32 v54, v51
	v_mov_b32_e32 v160, v51
	s_nop 1
	v_permlane16_swap_b32_e32 v54, v160
	v_mov_b32_e32 v57, v82
	v_mov_b32_e32 v58, v81
	v_lshlrev_b32_e32 v46, 16, v52
	v_and_b32_e32 v47, 0xffff0000, v52
	s_waitcnt lgkmcnt(0)
	v_add_f32_e32 v51, v54, v160
	s_nop 1
	v_mov_b32_dpp v54, v51 row_ror:8 row_mask:0xf bank_mask:0xf
	v_lshlrev_b32_e32 v52, 16, v53
	v_and_b32_e32 v53, 0xffff0000, v53
	s_waitcnt vmcnt(0)
	v_lshlrev_b32_e32 v74, 16, v64
	v_and_b32_e32 v75, 0xffff0000, v64
	s_waitcnt lgkmcnt(0)
	v_add_f32_e32 v51, v51, v54
	s_nop 1
	v_mov_b32_dpp v54, v51 row_ror:4 row_mask:0xf bank_mask:0xf
	v_lshlrev_b32_e32 v64, 16, v65
	v_and_b32_e32 v65, 0xffff0000, v65
	v_lshlrev_b32_e32 v76, 16, v66
	v_and_b32_e32 v77, 0xffff0000, v66
	s_waitcnt lgkmcnt(0)
	v_add_f32_e32 v51, v51, v54
	s_nop 1
	v_mov_b32_dpp v54, v51 row_ror:2 row_mask:0xf bank_mask:0xf
	v_lshlrev_b32_e32 v66, 16, v67
	v_and_b32_e32 v67, 0xffff0000, v67
	s_waitcnt lgkmcnt(0)
	v_add_f32_e32 v51, v51, v54
	s_nop 1
	v_mov_b32_dpp v54, v51 row_ror:1 row_mask:0xf bank_mask:0xf
	s_waitcnt lgkmcnt(0)
	v_add_f32_e32 v51, v51, v54
	v_fmamk_f32 v51, v51, 0x3a800000, v50
	v_mul_f32_e32 v54, 0x4b800000, v51
	v_cmp_gt_f32_e32 vcc, s7, v51
	s_nop 1
	v_cndmask_b32_e32 v51, v51, v54, vcc
	v_rsq_f32_e32 v51, v51
	s_nop 0
	v_mul_f32_e32 v54, 0x45800000, v51
	v_cndmask_b32_e32 v54, v51, v54, vcc
	v_pk_mul_f32 v[60:61], v[54:55], v[88:89] op_sel_hi:[0,1]
	v_pk_mul_f32 v[62:63], v[54:55], v[90:91] op_sel_hi:[0,1]
	v_pk_mul_f32 v[58:59], v[54:55], v[58:59] op_sel_hi:[0,1]
	v_pk_mul_f32 v[78:79], v[54:55], v[78:79] op_sel_hi:[0,1]
	v_pk_mul_f32 v[80:81], v[54:55], v[92:93] op_sel_hi:[0,1]
	v_pk_mul_f32 v[82:83], v[54:55], v[94:95] op_sel_hi:[0,1]
	v_pk_mul_f32 v[84:85], v[54:55], v[84:85] op_sel_hi:[0,1]
	v_pk_mul_f32 v[54:55], v[54:55], v[56:57] op_sel_hi:[0,1]
	v_pk_mul_f32 v[56:57], v[4:5], v[62:63]
	v_pk_mul_f32 v[60:61], v[6:7], v[60:61]
	v_pk_mul_f32 v[62:63], v[0:1], v[78:79]
	v_pk_mul_f32 v[58:59], v[2:3], v[58:59]
	v_pk_mul_f32 v[78:79], v[20:21], v[82:83]
	v_pk_mul_f32 v[80:81], v[22:23], v[80:81]
	v_pk_mul_f32 v[82:83], v[16:17], v[54:55]
	v_pk_mul_f32 v[84:85], v[18:19], v[84:85]
	v_pk_fma_f32 v[54:55], v[14:15], v[60:61], v[52:53]
	v_pk_fma_f32 v[52:53], v[12:13], v[56:57], v[46:47]
	v_pk_fma_f32 v[58:59], v[10:11], v[58:59], v[70:71]
	v_pk_fma_f32 v[56:57], v[8:9], v[62:63], v[68:69]
	v_pk_fma_f32 v[62:63], v[30:31], v[80:81], v[64:65]
	v_pk_fma_f32 v[60:61], v[28:29], v[78:79], v[74:75]
	v_pk_fma_f32 v[66:67], v[26:27], v[84:85], v[66:67]
	v_pk_fma_f32 v[64:65], v[24:25], v[82:83], v[76:77]
	global_store_dwordx4 v[72:73], v[52:55], off nt
	global_store_dwordx4 v[72:73], v[56:59], off offset:16 nt
	global_store_dwordx4 v[72:73], v[60:63], off offset:2048 nt
	global_store_dwordx4 v[72:73], v[64:67], off offset:2064 nt
	s_cbranch_scc0 .LBB0_1580
	v_add_u32_e32 v145, s4, v145
	v_cmp_lt_i32_e32 vcc, s8, v145
	s_or_b64 s[0:1], vcc, s[0:1]
	v_add_u32_e32 v48, s5, v48
	s_andn2_b64 exec, exec, s[0:1]
	s_cbranch_execnz .LBB0_1579
